# GEMM K-loops without the per-phase s_setprio flips (A/B of their deletion), on top of the census build
# speedup vs baseline: 1.0041x; 1.0041x over previous
.LBB0_136:
	s_add_u32 s50, s48, 0x100
	s_addc_u32 s51, s49, 0
	s_add_i32 s2, 0, 0x10000
	s_cmp_eq_u32 s33, 40
	s_cselect_b32 s61, s45, s51
	s_cselect_b32 s60, s44, s50
	v_add_u32_e32 v148, s2, v141
	s_cselect_b32 s27, s47, s83
	s_cselect_b32 s26, s46, s71
	s_add_i32 s4, 0, 0x14000
	ds_read_b128 v[144:147], v148
	ds_read_b128 v[156:159], v148 offset:1024
	ds_read_b128 v[160:163], v148 offset:2048
	ds_read_b128 v[164:167], v148 offset:3072
	v_add_u32_e32 v148, s4, v141
	ds_read_b128 v[168:171], v148
	ds_read_b128 v[172:175], v148 offset:1024
	ds_read_b128 v[176:179], v148 offset:2048
	ds_read_b128 v[180:183], v148 offset:3072
	v_lshl_add_u64 v[148:149], s[48:49], 0, v[136:137]
	s_add_i32 m0, s38, 0xc000
	ds_read_b128 v[184:187], v143
	ds_read_b128 v[188:191], v143 offset:1024
	ds_read_b128 v[192:195], v143 offset:2048
	ds_read_b128 v[196:199], v143 offset:3072
	ds_read_b128 v[200:203], v143 offset:4096
	ds_read_b128 v[204:207], v143 offset:5120
	ds_read_b128 v[208:211], v143 offset:6144
	ds_read_b128 v[212:215], v143 offset:7168
	global_load_lds_dwordx4 v[148:149], off
	v_lshl_add_u64 v[148:149], s[48:49], 0, v[138:139]
	s_add_i32 m0, s38, 0xe000
	s_nop 0
	global_load_lds_dwordx4 v[148:149], off
	s_waitcnt vmcnt(8)
	s_waitcnt lgkmcnt(0)
	s_barrier
	s_waitcnt lgkmcnt(0)
	v_mfma_f32_16x16x32_bf16 v[126:129], v[144:147], v[184:187], v[126:129]
	v_mfma_f32_16x16x32_bf16 v[122:125], v[160:163], v[184:187], v[122:125]
	v_mfma_f32_16x16x32_bf16 v[118:121], v[144:147], v[192:195], v[118:121]
	v_mfma_f32_16x16x32_bf16 v[114:117], v[160:163], v[192:195], v[114:117]
	v_mfma_f32_16x16x32_bf16 v[102:105], v[144:147], v[200:203], v[102:105]
	v_mfma_f32_16x16x32_bf16 v[98:101], v[160:163], v[200:203], v[98:101]
	v_mfma_f32_16x16x32_bf16 v[86:89], v[144:147], v[208:211], v[86:89]
	v_mfma_f32_16x16x32_bf16 v[82:85], v[160:163], v[208:211], v[82:85]
	v_mfma_f32_16x16x32_bf16 v[126:129], v[156:159], v[188:191], v[126:129]
	v_mfma_f32_16x16x32_bf16 v[122:125], v[164:167], v[188:191], v[122:125]
	v_mfma_f32_16x16x32_bf16 v[118:121], v[156:159], v[196:199], v[118:121]
	v_mfma_f32_16x16x32_bf16 v[114:117], v[164:167], v[196:199], v[114:117]
	v_mfma_f32_16x16x32_bf16 v[102:105], v[156:159], v[204:207], v[102:105]
	v_mfma_f32_16x16x32_bf16 v[98:101], v[164:167], v[204:207], v[98:101]
	v_mfma_f32_16x16x32_bf16 v[86:89], v[156:159], v[212:215], v[86:89]
	v_mfma_f32_16x16x32_bf16 v[82:85], v[164:167], v[212:215], v[82:85]
	v_mfma_f32_16x16x32_bf16 v[110:113], v[168:171], v[184:187], v[110:113]
	v_mfma_f32_16x16x32_bf16 v[106:109], v[176:179], v[184:187], v[106:109]
	v_mfma_f32_16x16x32_bf16 v[94:97], v[168:171], v[192:195], v[94:97]
	v_mfma_f32_16x16x32_bf16 v[90:93], v[176:179], v[192:195], v[90:93]
	v_mfma_f32_16x16x32_bf16 v[78:81], v[168:171], v[200:203], v[78:81]
	v_mfma_f32_16x16x32_bf16 v[74:77], v[176:179], v[200:203], v[74:77]
	v_mfma_f32_16x16x32_bf16 v[70:73], v[168:171], v[208:211], v[70:73]
	v_mfma_f32_16x16x32_bf16 v[66:69], v[176:179], v[208:211], v[66:69]
	v_mfma_f32_16x16x32_bf16 v[110:113], v[172:175], v[188:191], v[110:113]
	v_mfma_f32_16x16x32_bf16 v[106:109], v[180:183], v[188:191], v[106:109]
	v_mfma_f32_16x16x32_bf16 v[94:97], v[172:175], v[196:199], v[94:97]
	v_mfma_f32_16x16x32_bf16 v[90:93], v[180:183], v[196:199], v[90:93]
	v_mfma_f32_16x16x32_bf16 v[78:81], v[172:175], v[204:207], v[78:81]
	v_mfma_f32_16x16x32_bf16 v[74:77], v[180:183], v[204:207], v[74:77]
	v_mfma_f32_16x16x32_bf16 v[70:73], v[172:175], v[212:215], v[70:73]
	v_mfma_f32_16x16x32_bf16 v[66:69], v[180:183], v[212:215], v[66:69]
	s_barrier
	s_add_i32 s2, s2, s37
	v_lshl_add_u64 v[148:149], s[26:27], 0, v[0:1]
	s_mov_b32 m0, s2
	ds_read_b128 v[184:187], v143 offset:16384
	ds_read_b128 v[188:191], v143 offset:17408
	ds_read_b128 v[192:195], v143 offset:18432
	ds_read_b128 v[196:199], v143 offset:19456
	ds_read_b128 v[200:203], v143 offset:20480
	ds_read_b128 v[204:207], v143 offset:21504
	ds_read_b128 v[208:211], v143 offset:22528
	ds_read_b128 v[212:215], v143 offset:23552
	global_load_lds_dwordx4 v[148:149], off
	s_add_i32 m0, s2, 0x2000
	s_add_u32 s2, s26, 0xb0000
	v_lshl_add_u64 v[152:153], s[26:27], 0, v[134:135]
	s_addc_u32 s3, s27, 0
	s_add_i32 s4, s4, s37
	global_load_lds_dwordx4 v[152:153], off
	v_lshl_add_u64 v[154:155], s[2:3], 0, v[0:1]
	s_mov_b32 m0, s4
	v_lshl_add_u64 v[216:217], s[60:61], 0, v[132:133]
	global_load_lds_dwordx4 v[154:155], off
	v_lshl_add_u64 v[154:155], s[2:3], 0, v[134:135]
	s_add_i32 m0, s4, 0x2000
	s_nop 0
	global_load_lds_dwordx4 v[154:155], off
	v_lshl_add_u64 v[154:155], s[60:61], 0, v[130:131]
	s_mov_b32 m0, s38
	s_nop 0
	global_load_lds_dwordx4 v[154:155], off
	s_mov_b32 m0, s72
	s_nop 0
	global_load_lds_dwordx4 v[216:217], off
	s_waitcnt vmcnt(8)
	s_waitcnt lgkmcnt(0)
	s_barrier
	s_waitcnt lgkmcnt(0)
	v_mfma_f32_16x16x32_bf16 v[62:65], v[144:147], v[184:187], v[62:65]
	v_mfma_f32_16x16x32_bf16 v[58:61], v[160:163], v[184:187], v[58:61]
	v_mfma_f32_16x16x32_bf16 v[54:57], v[144:147], v[192:195], v[54:57]
	v_mfma_f32_16x16x32_bf16 v[50:53], v[160:163], v[192:195], v[50:53]
	v_mfma_f32_16x16x32_bf16 v[38:41], v[144:147], v[200:203], v[38:41]
	v_mfma_f32_16x16x32_bf16 v[34:37], v[160:163], v[200:203], v[34:37]
	v_mfma_f32_16x16x32_bf16 v[22:25], v[144:147], v[208:211], v[22:25]
	v_mfma_f32_16x16x32_bf16 v[18:21], v[160:163], v[208:211], v[18:21]
	v_mfma_f32_16x16x32_bf16 v[62:65], v[156:159], v[188:191], v[62:65]
	v_mfma_f32_16x16x32_bf16 v[58:61], v[164:167], v[188:191], v[58:61]
	v_mfma_f32_16x16x32_bf16 v[54:57], v[156:159], v[196:199], v[54:57]
	v_mfma_f32_16x16x32_bf16 v[50:53], v[164:167], v[196:199], v[50:53]
	v_mfma_f32_16x16x32_bf16 v[38:41], v[156:159], v[204:207], v[38:41]
	v_mfma_f32_16x16x32_bf16 v[34:37], v[164:167], v[204:207], v[34:37]
	v_mfma_f32_16x16x32_bf16 v[22:25], v[156:159], v[212:215], v[22:25]
	v_mfma_f32_16x16x32_bf16 v[18:21], v[164:167], v[212:215], v[18:21]
	v_mfma_f32_16x16x32_bf16 v[46:49], v[168:171], v[184:187], v[46:49]
	v_mfma_f32_16x16x32_bf16 v[42:45], v[176:179], v[184:187], v[42:45]
	v_mfma_f32_16x16x32_bf16 v[30:33], v[168:171], v[192:195], v[30:33]
	v_mfma_f32_16x16x32_bf16 v[26:29], v[176:179], v[192:195], v[26:29]
	v_mfma_f32_16x16x32_bf16 v[14:17], v[168:171], v[200:203], v[14:17]
	v_mfma_f32_16x16x32_bf16 v[10:13], v[176:179], v[200:203], v[10:13]
	v_mfma_f32_16x16x32_bf16 v[6:9], v[168:171], v[208:211], v[6:9]
	v_mfma_f32_16x16x32_bf16 v[2:5], v[176:179], v[208:211], v[2:5]
	v_mfma_f32_16x16x32_bf16 v[46:49], v[172:175], v[188:191], v[46:49]
	v_mfma_f32_16x16x32_bf16 v[42:45], v[180:183], v[188:191], v[42:45]
	v_mfma_f32_16x16x32_bf16 v[30:33], v[172:175], v[196:199], v[30:33]
	v_mfma_f32_16x16x32_bf16 v[26:29], v[180:183], v[196:199], v[26:29]
	v_mfma_f32_16x16x32_bf16 v[14:17], v[172:175], v[204:207], v[14:17]
	v_mfma_f32_16x16x32_bf16 v[10:13], v[180:183], v[204:207], v[10:13]
	v_mfma_f32_16x16x32_bf16 v[6:9], v[172:175], v[212:215], v[6:9]
	v_mfma_f32_16x16x32_bf16 v[2:5], v[180:183], v[212:215], v[2:5]
	s_barrier
	s_add_i32 s4, 0, 0x18000
	s_add_i32 s5, 0, 0x1c000
	v_add_u32_e32 v164, s4, v141
	v_add_u32_e32 v180, s5, v141
	ds_read_b128 v[144:147], v164
	ds_read_b128 v[156:159], v164 offset:1024
	ds_read_b128 v[160:163], v164 offset:2048
	ds_read_b128 v[164:167], v164 offset:3072
	ds_read_b128 v[168:171], v180
	ds_read_b128 v[172:175], v180 offset:1024
	ds_read_b128 v[176:179], v180 offset:2048
	ds_read_b128 v[180:183], v180 offset:3072
	s_add_u32 s2, s60, 0xb0000
	s_addc_u32 s3, s61, 0
	s_mov_b32 m0, s73
	v_lshl_add_u64 v[218:219], s[2:3], 0, v[130:131]
	ds_read_b128 v[184:187], v143 offset:32768
	ds_read_b128 v[188:191], v143 offset:33792
	ds_read_b128 v[192:195], v143 offset:34816
	ds_read_b128 v[196:199], v143 offset:35840
	ds_read_b128 v[200:203], v143 offset:36864
	ds_read_b128 v[204:207], v143 offset:37888
	ds_read_b128 v[208:211], v143 offset:38912
	ds_read_b128 v[212:215], v143 offset:39936
	global_load_lds_dwordx4 v[218:219], off
	v_lshl_add_u64 v[218:219], s[2:3], 0, v[132:133]
	s_mov_b32 m0, s76
	s_nop 0
	global_load_lds_dwordx4 v[218:219], off
	s_waitcnt vmcnt(8)
	s_waitcnt lgkmcnt(0)
	s_barrier
	s_waitcnt lgkmcnt(0)
	v_mfma_f32_16x16x32_bf16 v[126:129], v[144:147], v[184:187], v[126:129]
	v_mfma_f32_16x16x32_bf16 v[122:125], v[160:163], v[184:187], v[122:125]
	v_mfma_f32_16x16x32_bf16 v[118:121], v[144:147], v[192:195], v[118:121]
	v_mfma_f32_16x16x32_bf16 v[114:117], v[160:163], v[192:195], v[114:117]
	v_mfma_f32_16x16x32_bf16 v[102:105], v[144:147], v[200:203], v[102:105]
	v_mfma_f32_16x16x32_bf16 v[98:101], v[160:163], v[200:203], v[98:101]
	v_mfma_f32_16x16x32_bf16 v[86:89], v[144:147], v[208:211], v[86:89]
	v_mfma_f32_16x16x32_bf16 v[82:85], v[160:163], v[208:211], v[82:85]
	v_mfma_f32_16x16x32_bf16 v[126:129], v[156:159], v[188:191], v[126:129]
	v_mfma_f32_16x16x32_bf16 v[122:125], v[164:167], v[188:191], v[122:125]
	v_mfma_f32_16x16x32_bf16 v[118:121], v[156:159], v[196:199], v[118:121]
	v_mfma_f32_16x16x32_bf16 v[114:117], v[164:167], v[196:199], v[114:117]
	v_mfma_f32_16x16x32_bf16 v[102:105], v[156:159], v[204:207], v[102:105]
	v_mfma_f32_16x16x32_bf16 v[98:101], v[164:167], v[204:207], v[98:101]
	v_mfma_f32_16x16x32_bf16 v[86:89], v[156:159], v[212:215], v[86:89]
	v_mfma_f32_16x16x32_bf16 v[82:85], v[164:167], v[212:215], v[82:85]
	v_mfma_f32_16x16x32_bf16 v[110:113], v[168:171], v[184:187], v[110:113]
	v_mfma_f32_16x16x32_bf16 v[106:109], v[176:179], v[184:187], v[106:109]
	v_mfma_f32_16x16x32_bf16 v[94:97], v[168:171], v[192:195], v[94:97]
	v_mfma_f32_16x16x32_bf16 v[90:93], v[176:179], v[192:195], v[90:93]
	v_mfma_f32_16x16x32_bf16 v[78:81], v[168:171], v[200:203], v[78:81]
	v_mfma_f32_16x16x32_bf16 v[74:77], v[176:179], v[200:203], v[74:77]
	v_mfma_f32_16x16x32_bf16 v[70:73], v[168:171], v[208:211], v[70:73]
	v_mfma_f32_16x16x32_bf16 v[66:69], v[176:179], v[208:211], v[66:69]
	v_mfma_f32_16x16x32_bf16 v[110:113], v[172:175], v[188:191], v[110:113]
	v_mfma_f32_16x16x32_bf16 v[106:109], v[180:183], v[188:191], v[106:109]
	v_mfma_f32_16x16x32_bf16 v[94:97], v[172:175], v[196:199], v[94:97]
	v_mfma_f32_16x16x32_bf16 v[90:93], v[180:183], v[196:199], v[90:93]
	v_mfma_f32_16x16x32_bf16 v[78:81], v[172:175], v[204:207], v[78:81]
	v_mfma_f32_16x16x32_bf16 v[74:77], v[180:183], v[204:207], v[74:77]
	v_mfma_f32_16x16x32_bf16 v[70:73], v[172:175], v[212:215], v[70:73]
	v_mfma_f32_16x16x32_bf16 v[66:69], v[180:183], v[212:215], v[66:69]
	s_barrier
	s_add_i32 s2, s4, s37
	v_lshl_add_u64 v[148:149], v[148:149], 0, s[74:75]
	s_mov_b32 m0, s2
	ds_read_b128 v[184:187], v143 offset:49152
	ds_read_b128 v[188:191], v143 offset:50176
	ds_read_b128 v[192:195], v143 offset:51200
	ds_read_b128 v[196:199], v143 offset:52224
	ds_read_b128 v[200:203], v143 offset:53248
	ds_read_b128 v[204:207], v143 offset:54272
	ds_read_b128 v[208:211], v143 offset:55296
	ds_read_b128 v[212:215], v143 offset:56320
	global_load_lds_dwordx4 v[148:149], off
	s_add_i32 m0, s2, 0x2000
	s_add_u32 s2, s26, 0xb0080
	v_lshl_add_u64 v[148:149], v[152:153], 0, s[74:75]
	s_addc_u32 s3, s27, 0
	s_add_i32 s4, s5, s37
	global_load_lds_dwordx4 v[148:149], off
	v_lshl_add_u64 v[148:149], s[2:3], 0, v[0:1]
	s_mov_b32 m0, s4
	s_nop 0
	global_load_lds_dwordx4 v[148:149], off
	v_lshl_add_u64 v[148:149], s[2:3], 0, v[134:135]
	s_add_i32 m0, s4, 0x2000
	s_nop 0
	global_load_lds_dwordx4 v[148:149], off
	v_lshl_add_u64 v[148:149], v[154:155], 0, s[74:75]
	s_mov_b32 m0, s77
	s_nop 0
	global_load_lds_dwordx4 v[148:149], off
	v_lshl_add_u64 v[148:149], v[216:217], 0, s[74:75]
	s_mov_b32 m0, s78
	s_nop 0
	global_load_lds_dwordx4 v[148:149], off
	s_waitcnt vmcnt(8)
	s_waitcnt lgkmcnt(0)
	s_barrier
	s_waitcnt lgkmcnt(0)
	v_mfma_f32_16x16x32_bf16 v[62:65], v[144:147], v[184:187], v[62:65]
	v_mfma_f32_16x16x32_bf16 v[58:61], v[160:163], v[184:187], v[58:61]
	v_mfma_f32_16x16x32_bf16 v[54:57], v[144:147], v[192:195], v[54:57]
	v_mfma_f32_16x16x32_bf16 v[50:53], v[160:163], v[192:195], v[50:53]
	v_mfma_f32_16x16x32_bf16 v[38:41], v[144:147], v[200:203], v[38:41]
	v_mfma_f32_16x16x32_bf16 v[34:37], v[160:163], v[200:203], v[34:37]
	v_mfma_f32_16x16x32_bf16 v[22:25], v[144:147], v[208:211], v[22:25]
	v_mfma_f32_16x16x32_bf16 v[18:21], v[160:163], v[208:211], v[18:21]
	v_mfma_f32_16x16x32_bf16 v[62:65], v[156:159], v[188:191], v[62:65]
	v_mfma_f32_16x16x32_bf16 v[58:61], v[164:167], v[188:191], v[58:61]
	v_mfma_f32_16x16x32_bf16 v[54:57], v[156:159], v[196:199], v[54:57]
	v_mfma_f32_16x16x32_bf16 v[50:53], v[164:167], v[196:199], v[50:53]
	v_mfma_f32_16x16x32_bf16 v[38:41], v[156:159], v[204:207], v[38:41]
	v_mfma_f32_16x16x32_bf16 v[34:37], v[164:167], v[204:207], v[34:37]
	v_mfma_f32_16x16x32_bf16 v[22:25], v[156:159], v[212:215], v[22:25]
	v_mfma_f32_16x16x32_bf16 v[18:21], v[164:167], v[212:215], v[18:21]
	v_mfma_f32_16x16x32_bf16 v[46:49], v[168:171], v[184:187], v[46:49]
	v_mfma_f32_16x16x32_bf16 v[42:45], v[176:179], v[184:187], v[42:45]
	v_mfma_f32_16x16x32_bf16 v[30:33], v[168:171], v[192:195], v[30:33]
	v_mfma_f32_16x16x32_bf16 v[26:29], v[176:179], v[192:195], v[26:29]
	v_mfma_f32_16x16x32_bf16 v[14:17], v[168:171], v[200:203], v[14:17]
	v_mfma_f32_16x16x32_bf16 v[10:13], v[176:179], v[200:203], v[10:13]
	v_mfma_f32_16x16x32_bf16 v[6:9], v[168:171], v[208:211], v[6:9]
	v_mfma_f32_16x16x32_bf16 v[2:5], v[176:179], v[208:211], v[2:5]
	v_mfma_f32_16x16x32_bf16 v[46:49], v[172:175], v[188:191], v[46:49]
	v_mfma_f32_16x16x32_bf16 v[42:45], v[180:183], v[188:191], v[42:45]
	v_mfma_f32_16x16x32_bf16 v[30:33], v[172:175], v[196:199], v[30:33]
	v_mfma_f32_16x16x32_bf16 v[26:29], v[180:183], v[196:199], v[26:29]
	v_mfma_f32_16x16x32_bf16 v[14:17], v[172:175], v[204:207], v[14:17]
	v_mfma_f32_16x16x32_bf16 v[10:13], v[180:183], v[204:207], v[10:13]
	v_mfma_f32_16x16x32_bf16 v[6:9], v[172:175], v[212:215], v[6:9]
	v_mfma_f32_16x16x32_bf16 v[2:5], v[180:183], v[212:215], v[2:5]
	s_barrier
	s_add_i32 s33, s33, 2
	s_add_u32 s71, s71, 0x100
	s_addc_u32 s83, s83, 0
	s_cmp_gt_u32 s33, 41
	s_mov_b64 s[48:49], s[50:51]
	s_cbranch_scc0 .LBB0_136
	s_and_b64 vcc, exec, s[34:35]
	s_cbranch_vccz .LBB0_139
	s_barrier

.LBB0_148:
	s_add_i32 s46, s26, 2
	s_mov_b32 s47, s21
	s_or_b32 s20, s26, 1
	s_lshl_b64 s[2:3], s[46:47], 7
	s_cmp_lg_u32 s26, s71
	s_cselect_b32 s2, s2, 0
	s_cselect_b32 s3, s3, 0
	s_add_u32 s48, s42, s2
	s_addc_u32 s49, s43, s3
	s_add_i32 s4, 0, 0x10000
	s_add_u32 s26, s34, s2
	v_add_u32_e32 v148, s4, v138
	s_addc_u32 s27, s35, s3
	s_add_i32 s5, 0, 0x14000
	ds_read_b128 v[140:143], v148
	ds_read_b128 v[144:147], v148 offset:1024
	ds_read_b128 v[156:159], v148 offset:2048
	ds_read_b128 v[160:163], v148 offset:3072
	v_add_u32_e32 v148, s5, v138
	ds_read_b128 v[164:167], v148
	ds_read_b128 v[168:171], v148 offset:1024
	ds_read_b128 v[172:175], v148 offset:2048
	ds_read_b128 v[176:179], v148 offset:3072
	s_lshl_b64 s[2:3], s[20:21], 7
	s_add_u32 s2, s44, s2
	s_addc_u32 s3, s45, s3
	v_lshl_add_u64 v[148:149], s[2:3], 0, v[134:135]
	s_add_i32 m0, s51, 0xc000
	ds_read_b128 v[180:183], v139
	ds_read_b128 v[184:187], v139 offset:1024
	ds_read_b128 v[188:191], v139 offset:2048
	ds_read_b128 v[192:195], v139 offset:3072
	ds_read_b128 v[196:199], v139 offset:4096
	ds_read_b128 v[200:203], v139 offset:5120
	ds_read_b128 v[204:207], v139 offset:6144
	ds_read_b128 v[208:211], v139 offset:7168
	global_load_lds_dwordx4 v[148:149], off
	v_lshl_add_u64 v[148:149], s[2:3], 0, v[132:133]
	s_add_i32 m0, s51, 0xe000
	s_nop 0
	global_load_lds_dwordx4 v[148:149], off
	s_waitcnt vmcnt(8)
	s_waitcnt lgkmcnt(0)
	s_barrier
	s_waitcnt lgkmcnt(0)
	v_mfma_f32_16x16x32_bf16 v[126:129], v[140:143], v[180:183], v[126:129]
	v_mfma_f32_16x16x32_bf16 v[122:125], v[156:159], v[180:183], v[122:125]
	v_mfma_f32_16x16x32_bf16 v[118:121], v[140:143], v[188:191], v[118:121]
	v_mfma_f32_16x16x32_bf16 v[114:117], v[156:159], v[188:191], v[114:117]
	v_mfma_f32_16x16x32_bf16 v[106:109], v[140:143], v[196:199], v[106:109]
	v_mfma_f32_16x16x32_bf16 v[98:101], v[156:159], v[196:199], v[98:101]
	v_mfma_f32_16x16x32_bf16 v[90:93], v[140:143], v[204:207], v[90:93]
	v_mfma_f32_16x16x32_bf16 v[82:85], v[156:159], v[204:207], v[82:85]
	v_mfma_f32_16x16x32_bf16 v[126:129], v[144:147], v[184:187], v[126:129]
	v_mfma_f32_16x16x32_bf16 v[122:125], v[160:163], v[184:187], v[122:125]
	v_mfma_f32_16x16x32_bf16 v[118:121], v[144:147], v[192:195], v[118:121]
	v_mfma_f32_16x16x32_bf16 v[114:117], v[160:163], v[192:195], v[114:117]
	v_mfma_f32_16x16x32_bf16 v[106:109], v[144:147], v[200:203], v[106:109]
	v_mfma_f32_16x16x32_bf16 v[98:101], v[160:163], v[200:203], v[98:101]
	v_mfma_f32_16x16x32_bf16 v[90:93], v[144:147], v[208:211], v[90:93]
	v_mfma_f32_16x16x32_bf16 v[82:85], v[160:163], v[208:211], v[82:85]
	v_mfma_f32_16x16x32_bf16 v[110:113], v[164:167], v[180:183], v[110:113]
	v_mfma_f32_16x16x32_bf16 v[102:105], v[172:175], v[180:183], v[102:105]
	v_mfma_f32_16x16x32_bf16 v[94:97], v[164:167], v[188:191], v[94:97]
	v_mfma_f32_16x16x32_bf16 v[86:89], v[172:175], v[188:191], v[86:89]
	v_mfma_f32_16x16x32_bf16 v[78:81], v[164:167], v[196:199], v[78:81]
	v_mfma_f32_16x16x32_bf16 v[74:77], v[172:175], v[196:199], v[74:77]
	v_mfma_f32_16x16x32_bf16 v[70:73], v[164:167], v[204:207], v[70:73]
	v_mfma_f32_16x16x32_bf16 v[66:69], v[172:175], v[204:207], v[66:69]
	v_mfma_f32_16x16x32_bf16 v[110:113], v[168:171], v[184:187], v[110:113]
	v_mfma_f32_16x16x32_bf16 v[102:105], v[176:179], v[184:187], v[102:105]
	v_mfma_f32_16x16x32_bf16 v[94:97], v[168:171], v[192:195], v[94:97]
	v_mfma_f32_16x16x32_bf16 v[86:89], v[176:179], v[192:195], v[86:89]
	v_mfma_f32_16x16x32_bf16 v[78:81], v[168:171], v[200:203], v[78:81]
	v_mfma_f32_16x16x32_bf16 v[74:77], v[176:179], v[200:203], v[74:77]
	v_mfma_f32_16x16x32_bf16 v[70:73], v[168:171], v[208:211], v[70:73]
	v_mfma_f32_16x16x32_bf16 v[66:69], v[176:179], v[208:211], v[66:69]
	s_barrier
	s_add_i32 s2, s4, s50
	v_lshl_add_u64 v[148:149], s[26:27], 0, v[0:1]
	s_mov_b32 m0, s2
	ds_read_b128 v[180:183], v139 offset:16384
	ds_read_b128 v[184:187], v139 offset:17408
	ds_read_b128 v[188:191], v139 offset:18432
	ds_read_b128 v[192:195], v139 offset:19456
	ds_read_b128 v[196:199], v139 offset:20480
	ds_read_b128 v[200:203], v139 offset:21504
	ds_read_b128 v[204:207], v139 offset:22528
	ds_read_b128 v[208:211], v139 offset:23552
	global_load_lds_dwordx4 v[148:149], off
	s_add_i32 m0, s2, 0x2000
	s_add_u32 s2, s26, 0xb0000
	v_lshl_add_u64 v[152:153], s[26:27], 0, v[130:131]
	s_addc_u32 s3, s27, 0
	s_add_i32 s4, s5, s50
	global_load_lds_dwordx4 v[152:153], off
	v_lshl_add_u64 v[154:155], s[2:3], 0, v[0:1]
	s_mov_b32 m0, s4
	v_lshl_add_u64 v[212:213], s[48:49], 0, v[132:133]
	global_load_lds_dwordx4 v[154:155], off
	v_lshl_add_u64 v[154:155], s[2:3], 0, v[130:131]
	s_add_i32 m0, s4, 0x2000
	s_nop 0
	global_load_lds_dwordx4 v[154:155], off
	v_lshl_add_u64 v[154:155], s[48:49], 0, v[134:135]
	s_mov_b32 m0, s51
	s_nop 0
	global_load_lds_dwordx4 v[154:155], off
	s_mov_b32 m0, s60
	s_nop 0
	global_load_lds_dwordx4 v[212:213], off
	s_waitcnt vmcnt(8)
	s_waitcnt lgkmcnt(0)
	s_barrier
	s_waitcnt lgkmcnt(0)
	v_mfma_f32_16x16x32_bf16 v[62:65], v[140:143], v[180:183], v[62:65]
	v_mfma_f32_16x16x32_bf16 v[58:61], v[156:159], v[180:183], v[58:61]
	v_mfma_f32_16x16x32_bf16 v[54:57], v[140:143], v[188:191], v[54:57]
	v_mfma_f32_16x16x32_bf16 v[50:53], v[156:159], v[188:191], v[50:53]
	v_mfma_f32_16x16x32_bf16 v[38:41], v[140:143], v[196:199], v[38:41]
	v_mfma_f32_16x16x32_bf16 v[34:37], v[156:159], v[196:199], v[34:37]
	v_mfma_f32_16x16x32_bf16 v[22:25], v[140:143], v[204:207], v[22:25]
	v_mfma_f32_16x16x32_bf16 v[18:21], v[156:159], v[204:207], v[18:21]
	v_mfma_f32_16x16x32_bf16 v[62:65], v[144:147], v[184:187], v[62:65]
	v_mfma_f32_16x16x32_bf16 v[58:61], v[160:163], v[184:187], v[58:61]
	v_mfma_f32_16x16x32_bf16 v[54:57], v[144:147], v[192:195], v[54:57]
	v_mfma_f32_16x16x32_bf16 v[50:53], v[160:163], v[192:195], v[50:53]
	v_mfma_f32_16x16x32_bf16 v[38:41], v[144:147], v[200:203], v[38:41]
	v_mfma_f32_16x16x32_bf16 v[34:37], v[160:163], v[200:203], v[34:37]
	v_mfma_f32_16x16x32_bf16 v[22:25], v[144:147], v[208:211], v[22:25]
	v_mfma_f32_16x16x32_bf16 v[18:21], v[160:163], v[208:211], v[18:21]
	v_mfma_f32_16x16x32_bf16 v[46:49], v[164:167], v[180:183], v[46:49]
	v_mfma_f32_16x16x32_bf16 v[42:45], v[172:175], v[180:183], v[42:45]
	v_mfma_f32_16x16x32_bf16 v[30:33], v[164:167], v[188:191], v[30:33]
	v_mfma_f32_16x16x32_bf16 v[26:29], v[172:175], v[188:191], v[26:29]
	v_mfma_f32_16x16x32_bf16 v[14:17], v[164:167], v[196:199], v[14:17]
	v_mfma_f32_16x16x32_bf16 v[10:13], v[172:175], v[196:199], v[10:13]
	v_mfma_f32_16x16x32_bf16 v[6:9], v[164:167], v[204:207], v[6:9]
	v_mfma_f32_16x16x32_bf16 v[2:5], v[172:175], v[204:207], v[2:5]
	v_mfma_f32_16x16x32_bf16 v[46:49], v[168:171], v[184:187], v[46:49]
	v_mfma_f32_16x16x32_bf16 v[42:45], v[176:179], v[184:187], v[42:45]
	v_mfma_f32_16x16x32_bf16 v[30:33], v[168:171], v[192:195], v[30:33]
	v_mfma_f32_16x16x32_bf16 v[26:29], v[176:179], v[192:195], v[26:29]
	v_mfma_f32_16x16x32_bf16 v[14:17], v[168:171], v[200:203], v[14:17]
	v_mfma_f32_16x16x32_bf16 v[10:13], v[176:179], v[200:203], v[10:13]
	v_mfma_f32_16x16x32_bf16 v[6:9], v[168:171], v[208:211], v[6:9]
	v_mfma_f32_16x16x32_bf16 v[2:5], v[176:179], v[208:211], v[2:5]
	s_barrier
	s_add_i32 s4, 0, 0x18000
	s_add_i32 s5, 0, 0x1c000
	v_add_u32_e32 v160, s4, v138
	v_add_u32_e32 v176, s5, v138
	ds_read_b128 v[140:143], v160
	ds_read_b128 v[144:147], v160 offset:1024
	ds_read_b128 v[156:159], v160 offset:2048
	ds_read_b128 v[160:163], v160 offset:3072
	ds_read_b128 v[164:167], v176
	ds_read_b128 v[168:171], v176 offset:1024
	ds_read_b128 v[172:175], v176 offset:2048
	ds_read_b128 v[176:179], v176 offset:3072
	s_add_u32 s2, s48, 0xb0000
	s_addc_u32 s3, s49, 0
	s_mov_b32 m0, s61
	v_lshl_add_u64 v[214:215], s[2:3], 0, v[134:135]
	ds_read_b128 v[180:183], v139 offset:32768
	ds_read_b128 v[184:187], v139 offset:33792
	ds_read_b128 v[188:191], v139 offset:34816
	ds_read_b128 v[192:195], v139 offset:35840
	ds_read_b128 v[196:199], v139 offset:36864
	ds_read_b128 v[200:203], v139 offset:37888
	ds_read_b128 v[204:207], v139 offset:38912
	ds_read_b128 v[208:211], v139 offset:39936
	global_load_lds_dwordx4 v[214:215], off
	v_lshl_add_u64 v[214:215], s[2:3], 0, v[132:133]
	s_mov_b32 m0, s72
	s_nop 0
	global_load_lds_dwordx4 v[214:215], off
	s_waitcnt vmcnt(8)
	s_waitcnt lgkmcnt(0)
	s_barrier
	s_waitcnt lgkmcnt(0)
	v_mfma_f32_16x16x32_bf16 v[126:129], v[140:143], v[180:183], v[126:129]
	v_mfma_f32_16x16x32_bf16 v[122:125], v[156:159], v[180:183], v[122:125]
	v_mfma_f32_16x16x32_bf16 v[118:121], v[140:143], v[188:191], v[118:121]
	v_mfma_f32_16x16x32_bf16 v[114:117], v[156:159], v[188:191], v[114:117]
	v_mfma_f32_16x16x32_bf16 v[106:109], v[140:143], v[196:199], v[106:109]
	v_mfma_f32_16x16x32_bf16 v[98:101], v[156:159], v[196:199], v[98:101]
	v_mfma_f32_16x16x32_bf16 v[90:93], v[140:143], v[204:207], v[90:93]
	v_mfma_f32_16x16x32_bf16 v[82:85], v[156:159], v[204:207], v[82:85]
	v_mfma_f32_16x16x32_bf16 v[126:129], v[144:147], v[184:187], v[126:129]
	v_mfma_f32_16x16x32_bf16 v[122:125], v[160:163], v[184:187], v[122:125]
	v_mfma_f32_16x16x32_bf16 v[118:121], v[144:147], v[192:195], v[118:121]
	v_mfma_f32_16x16x32_bf16 v[114:117], v[160:163], v[192:195], v[114:117]
	v_mfma_f32_16x16x32_bf16 v[106:109], v[144:147], v[200:203], v[106:109]
	v_mfma_f32_16x16x32_bf16 v[98:101], v[160:163], v[200:203], v[98:101]
	v_mfma_f32_16x16x32_bf16 v[90:93], v[144:147], v[208:211], v[90:93]
	v_mfma_f32_16x16x32_bf16 v[82:85], v[160:163], v[208:211], v[82:85]
	v_mfma_f32_16x16x32_bf16 v[110:113], v[164:167], v[180:183], v[110:113]
	v_mfma_f32_16x16x32_bf16 v[102:105], v[172:175], v[180:183], v[102:105]
	v_mfma_f32_16x16x32_bf16 v[94:97], v[164:167], v[188:191], v[94:97]
	v_mfma_f32_16x16x32_bf16 v[86:89], v[172:175], v[188:191], v[86:89]
	v_mfma_f32_16x16x32_bf16 v[78:81], v[164:167], v[196:199], v[78:81]
	v_mfma_f32_16x16x32_bf16 v[74:77], v[172:175], v[196:199], v[74:77]
	v_mfma_f32_16x16x32_bf16 v[70:73], v[164:167], v[204:207], v[70:73]
	v_mfma_f32_16x16x32_bf16 v[66:69], v[172:175], v[204:207], v[66:69]
	v_mfma_f32_16x16x32_bf16 v[110:113], v[168:171], v[184:187], v[110:113]
	v_mfma_f32_16x16x32_bf16 v[102:105], v[176:179], v[184:187], v[102:105]
	v_mfma_f32_16x16x32_bf16 v[94:97], v[168:171], v[192:195], v[94:97]
	v_mfma_f32_16x16x32_bf16 v[86:89], v[176:179], v[192:195], v[86:89]
	v_mfma_f32_16x16x32_bf16 v[78:81], v[168:171], v[200:203], v[78:81]
	v_mfma_f32_16x16x32_bf16 v[74:77], v[176:179], v[200:203], v[74:77]
	v_mfma_f32_16x16x32_bf16 v[70:73], v[168:171], v[208:211], v[70:73]
	v_mfma_f32_16x16x32_bf16 v[66:69], v[176:179], v[208:211], v[66:69]
	s_barrier
	s_add_i32 s2, s4, s50
	v_lshl_add_u64 v[148:149], v[148:149], 0, s[74:75]
	s_mov_b32 m0, s2
	ds_read_b128 v[180:183], v139 offset:49152
	ds_read_b128 v[184:187], v139 offset:50176
	ds_read_b128 v[188:191], v139 offset:51200
	ds_read_b128 v[192:195], v139 offset:52224
	ds_read_b128 v[196:199], v139 offset:53248
	ds_read_b128 v[200:203], v139 offset:54272
	ds_read_b128 v[204:207], v139 offset:55296
	ds_read_b128 v[208:211], v139 offset:56320
	global_load_lds_dwordx4 v[148:149], off
	s_add_i32 m0, s2, 0x2000
	s_add_u32 s2, s26, 0xb0080
	v_lshl_add_u64 v[148:149], v[152:153], 0, s[74:75]
	s_addc_u32 s3, s27, 0
	s_add_i32 s4, s5, s50
	global_load_lds_dwordx4 v[148:149], off
	v_lshl_add_u64 v[148:149], s[2:3], 0, v[0:1]
	s_mov_b32 m0, s4
	s_nop 0
	global_load_lds_dwordx4 v[148:149], off
	v_lshl_add_u64 v[148:149], s[2:3], 0, v[130:131]
	s_add_i32 m0, s4, 0x2000
	s_nop 0
	global_load_lds_dwordx4 v[148:149], off
	v_lshl_add_u64 v[148:149], v[154:155], 0, s[74:75]
	s_mov_b32 m0, s77
	s_nop 0
	global_load_lds_dwordx4 v[148:149], off
	v_lshl_add_u64 v[148:149], v[212:213], 0, s[74:75]
	s_mov_b32 m0, s78
	s_nop 0
	global_load_lds_dwordx4 v[148:149], off
	s_waitcnt vmcnt(8)
	s_waitcnt lgkmcnt(0)
	s_barrier
	s_waitcnt lgkmcnt(0)
	v_mfma_f32_16x16x32_bf16 v[62:65], v[140:143], v[180:183], v[62:65]
	v_mfma_f32_16x16x32_bf16 v[58:61], v[156:159], v[180:183], v[58:61]
	v_mfma_f32_16x16x32_bf16 v[54:57], v[140:143], v[188:191], v[54:57]
	v_mfma_f32_16x16x32_bf16 v[50:53], v[156:159], v[188:191], v[50:53]
	v_mfma_f32_16x16x32_bf16 v[38:41], v[140:143], v[196:199], v[38:41]
	v_mfma_f32_16x16x32_bf16 v[34:37], v[156:159], v[196:199], v[34:37]
	v_mfma_f32_16x16x32_bf16 v[22:25], v[140:143], v[204:207], v[22:25]
	v_mfma_f32_16x16x32_bf16 v[18:21], v[156:159], v[204:207], v[18:21]
	v_mfma_f32_16x16x32_bf16 v[62:65], v[144:147], v[184:187], v[62:65]
	v_mfma_f32_16x16x32_bf16 v[58:61], v[160:163], v[184:187], v[58:61]
	v_mfma_f32_16x16x32_bf16 v[54:57], v[144:147], v[192:195], v[54:57]
	v_mfma_f32_16x16x32_bf16 v[50:53], v[160:163], v[192:195], v[50:53]
	v_mfma_f32_16x16x32_bf16 v[38:41], v[144:147], v[200:203], v[38:41]
	v_mfma_f32_16x16x32_bf16 v[34:37], v[160:163], v[200:203], v[34:37]
	v_mfma_f32_16x16x32_bf16 v[22:25], v[144:147], v[208:211], v[22:25]
	v_mfma_f32_16x16x32_bf16 v[18:21], v[160:163], v[208:211], v[18:21]
	v_mfma_f32_16x16x32_bf16 v[46:49], v[164:167], v[180:183], v[46:49]
	v_mfma_f32_16x16x32_bf16 v[42:45], v[172:175], v[180:183], v[42:45]
	v_mfma_f32_16x16x32_bf16 v[30:33], v[164:167], v[188:191], v[30:33]
	v_mfma_f32_16x16x32_bf16 v[26:29], v[172:175], v[188:191], v[26:29]
	v_mfma_f32_16x16x32_bf16 v[14:17], v[164:167], v[196:199], v[14:17]
	v_mfma_f32_16x16x32_bf16 v[10:13], v[172:175], v[196:199], v[10:13]
	v_mfma_f32_16x16x32_bf16 v[6:9], v[164:167], v[204:207], v[6:9]
	v_mfma_f32_16x16x32_bf16 v[2:5], v[172:175], v[204:207], v[2:5]
	v_mfma_f32_16x16x32_bf16 v[46:49], v[168:171], v[184:187], v[46:49]
	v_mfma_f32_16x16x32_bf16 v[42:45], v[176:179], v[184:187], v[42:45]
	v_mfma_f32_16x16x32_bf16 v[30:33], v[168:171], v[192:195], v[30:33]
	v_mfma_f32_16x16x32_bf16 v[26:29], v[176:179], v[192:195], v[26:29]
	v_mfma_f32_16x16x32_bf16 v[14:17], v[168:171], v[200:203], v[14:17]
	v_mfma_f32_16x16x32_bf16 v[10:13], v[176:179], v[200:203], v[10:13]
	v_mfma_f32_16x16x32_bf16 v[6:9], v[168:171], v[208:211], v[6:9]
	v_mfma_f32_16x16x32_bf16 v[2:5], v[176:179], v[208:211], v[2:5]
	s_barrier
	s_cmp_ge_u32 s46, s76
	s_mov_b32 s26, s46
	s_cbranch_scc0 .LBB0_148
	s_cmpk_lt_u32 s25, 0x100
	v_readlane_b32 s71, v250, 15
	v_readlane_b32 s78, v249, 35
	s_mov_b64 s[76:77], s[40:41]
	s_cbranch_scc0 .LBB0_151
	s_barrier

.LBB0_163:
	s_add_u32 s2, s96, 0xfffc0080
	s_addc_u32 s3, s97, -1
	s_add_i32 s4, 0, 0x10000
	s_cmp_eq_u32 s33, 12
	s_cselect_b32 vcc_hi, s47, s3
	s_cselect_b32 vcc_lo, s81, s2
	v_add_u32_e32 v148, s4, v141
	s_cselect_b32 s27, s45, s71
	s_cselect_b32 s26, s82, s83
	s_add_i32 s5, 0, 0x14000
	ds_read_b128 v[144:147], v148
	ds_read_b128 v[156:159], v148 offset:1024
	ds_read_b128 v[160:163], v148 offset:2048
	ds_read_b128 v[164:167], v148 offset:3072
	v_add_u32_e32 v148, s5, v141
	ds_read_b128 v[168:171], v148
	ds_read_b128 v[172:175], v148 offset:1024
	ds_read_b128 v[176:179], v148 offset:2048
	ds_read_b128 v[180:183], v148 offset:3072
	v_lshl_add_u64 v[148:149], s[96:97], 0, v[136:137]
	s_add_i32 m0, s38, 0xc000
	ds_read_b128 v[184:187], v143
	ds_read_b128 v[188:191], v143 offset:1024
	ds_read_b128 v[192:195], v143 offset:2048
	ds_read_b128 v[196:199], v143 offset:3072
	ds_read_b128 v[200:203], v143 offset:4096
	ds_read_b128 v[204:207], v143 offset:5120
	ds_read_b128 v[208:211], v143 offset:6144
	ds_read_b128 v[212:215], v143 offset:7168
	global_load_lds_dwordx4 v[148:149], off
	v_lshl_add_u64 v[148:149], s[96:97], 0, v[138:139]
	s_add_i32 m0, s38, 0xe000
	s_nop 0
	global_load_lds_dwordx4 v[148:149], off
	s_waitcnt vmcnt(8)
	s_waitcnt lgkmcnt(0)
	s_barrier
	s_waitcnt lgkmcnt(0)
	v_mfma_f32_16x16x32_bf16 v[126:129], v[144:147], v[184:187], v[126:129]
	v_mfma_f32_16x16x32_bf16 v[122:125], v[160:163], v[184:187], v[122:125]
	v_mfma_f32_16x16x32_bf16 v[110:113], v[144:147], v[192:195], v[110:113]
	v_mfma_f32_16x16x32_bf16 v[106:109], v[160:163], v[192:195], v[106:109]
	v_mfma_f32_16x16x32_bf16 v[94:97], v[144:147], v[200:203], v[94:97]
	v_mfma_f32_16x16x32_bf16 v[90:93], v[160:163], v[200:203], v[90:93]
	v_mfma_f32_16x16x32_bf16 v[78:81], v[144:147], v[208:211], v[78:81]
	v_mfma_f32_16x16x32_bf16 v[74:77], v[160:163], v[208:211], v[74:77]
	v_mfma_f32_16x16x32_bf16 v[126:129], v[156:159], v[188:191], v[126:129]
	v_mfma_f32_16x16x32_bf16 v[122:125], v[164:167], v[188:191], v[122:125]
	v_mfma_f32_16x16x32_bf16 v[110:113], v[156:159], v[196:199], v[110:113]
	v_mfma_f32_16x16x32_bf16 v[106:109], v[164:167], v[196:199], v[106:109]
	v_mfma_f32_16x16x32_bf16 v[94:97], v[156:159], v[204:207], v[94:97]
	v_mfma_f32_16x16x32_bf16 v[90:93], v[164:167], v[204:207], v[90:93]
	v_mfma_f32_16x16x32_bf16 v[78:81], v[156:159], v[212:215], v[78:81]
	v_mfma_f32_16x16x32_bf16 v[74:77], v[164:167], v[212:215], v[74:77]
	v_mfma_f32_16x16x32_bf16 v[118:121], v[168:171], v[184:187], v[118:121]
	v_mfma_f32_16x16x32_bf16 v[114:117], v[176:179], v[184:187], v[114:117]
	v_mfma_f32_16x16x32_bf16 v[102:105], v[168:171], v[192:195], v[102:105]
	v_mfma_f32_16x16x32_bf16 v[98:101], v[176:179], v[192:195], v[98:101]
	v_mfma_f32_16x16x32_bf16 v[86:89], v[168:171], v[200:203], v[86:89]
	v_mfma_f32_16x16x32_bf16 v[82:85], v[176:179], v[200:203], v[82:85]
	v_mfma_f32_16x16x32_bf16 v[70:73], v[168:171], v[208:211], v[70:73]
	v_mfma_f32_16x16x32_bf16 v[66:69], v[176:179], v[208:211], v[66:69]
	v_mfma_f32_16x16x32_bf16 v[118:121], v[172:175], v[188:191], v[118:121]
	v_mfma_f32_16x16x32_bf16 v[114:117], v[180:183], v[188:191], v[114:117]
	v_mfma_f32_16x16x32_bf16 v[102:105], v[172:175], v[196:199], v[102:105]
	v_mfma_f32_16x16x32_bf16 v[98:101], v[180:183], v[196:199], v[98:101]
	v_mfma_f32_16x16x32_bf16 v[86:89], v[172:175], v[204:207], v[86:89]
	v_mfma_f32_16x16x32_bf16 v[82:85], v[180:183], v[204:207], v[82:85]
	v_mfma_f32_16x16x32_bf16 v[70:73], v[172:175], v[212:215], v[70:73]
	v_mfma_f32_16x16x32_bf16 v[66:69], v[180:183], v[212:215], v[66:69]
	s_barrier
	s_add_i32 s2, s4, s31
	v_lshl_add_u64 v[148:149], s[26:27], 0, v[0:1]
	s_mov_b32 m0, s2
	ds_read_b128 v[184:187], v143 offset:16384
	ds_read_b128 v[188:191], v143 offset:17408
	ds_read_b128 v[192:195], v143 offset:18432
	ds_read_b128 v[196:199], v143 offset:19456
	ds_read_b128 v[200:203], v143 offset:20480
	ds_read_b128 v[204:207], v143 offset:21504
	ds_read_b128 v[208:211], v143 offset:22528
	ds_read_b128 v[212:215], v143 offset:23552
	global_load_lds_dwordx4 v[148:149], off
	s_add_i32 m0, s2, 0x2000
	s_add_u32 s2, s26, 0x40000
	v_lshl_add_u64 v[152:153], s[26:27], 0, v[130:131]
	s_addc_u32 s3, s27, 0
	s_add_i32 s4, s5, s31
	global_load_lds_dwordx4 v[152:153], off
	v_lshl_add_u64 v[154:155], s[2:3], 0, v[0:1]
	s_mov_b32 m0, s4
	v_lshl_add_u64 v[216:217], vcc, 0, v[132:133]
	global_load_lds_dwordx4 v[154:155], off
	v_lshl_add_u64 v[154:155], s[2:3], 0, v[130:131]
	s_add_i32 m0, s4, 0x2000
	s_nop 0
	global_load_lds_dwordx4 v[154:155], off
	v_lshl_add_u64 v[154:155], vcc, 0, v[134:135]
	s_mov_b32 m0, s38
	s_nop 0
	global_load_lds_dwordx4 v[154:155], off
	s_mov_b32 m0, s61
	s_nop 0
	global_load_lds_dwordx4 v[216:217], off
	s_waitcnt vmcnt(8)
	s_waitcnt lgkmcnt(0)
	s_barrier
	s_waitcnt lgkmcnt(0)
	v_mfma_f32_16x16x32_bf16 v[62:65], v[144:147], v[184:187], v[62:65]
	v_mfma_f32_16x16x32_bf16 v[58:61], v[160:163], v[184:187], v[58:61]
	v_mfma_f32_16x16x32_bf16 v[46:49], v[144:147], v[192:195], v[46:49]
	v_mfma_f32_16x16x32_bf16 v[42:45], v[160:163], v[192:195], v[42:45]
	v_mfma_f32_16x16x32_bf16 v[30:33], v[144:147], v[200:203], v[30:33]
	v_mfma_f32_16x16x32_bf16 v[26:29], v[160:163], v[200:203], v[26:29]
	v_mfma_f32_16x16x32_bf16 v[14:17], v[144:147], v[208:211], v[14:17]
	v_mfma_f32_16x16x32_bf16 v[10:13], v[160:163], v[208:211], v[10:13]
	v_mfma_f32_16x16x32_bf16 v[62:65], v[156:159], v[188:191], v[62:65]
	v_mfma_f32_16x16x32_bf16 v[58:61], v[164:167], v[188:191], v[58:61]
	v_mfma_f32_16x16x32_bf16 v[46:49], v[156:159], v[196:199], v[46:49]
	v_mfma_f32_16x16x32_bf16 v[42:45], v[164:167], v[196:199], v[42:45]
	v_mfma_f32_16x16x32_bf16 v[30:33], v[156:159], v[204:207], v[30:33]
	v_mfma_f32_16x16x32_bf16 v[26:29], v[164:167], v[204:207], v[26:29]
	v_mfma_f32_16x16x32_bf16 v[14:17], v[156:159], v[212:215], v[14:17]
	v_mfma_f32_16x16x32_bf16 v[10:13], v[164:167], v[212:215], v[10:13]
	v_mfma_f32_16x16x32_bf16 v[54:57], v[168:171], v[184:187], v[54:57]
	v_mfma_f32_16x16x32_bf16 v[50:53], v[176:179], v[184:187], v[50:53]
	v_mfma_f32_16x16x32_bf16 v[38:41], v[168:171], v[192:195], v[38:41]
	v_mfma_f32_16x16x32_bf16 v[34:37], v[176:179], v[192:195], v[34:37]
	v_mfma_f32_16x16x32_bf16 v[22:25], v[168:171], v[200:203], v[22:25]
	v_mfma_f32_16x16x32_bf16 v[18:21], v[176:179], v[200:203], v[18:21]
	v_mfma_f32_16x16x32_bf16 v[6:9], v[168:171], v[208:211], v[6:9]
	v_mfma_f32_16x16x32_bf16 v[2:5], v[176:179], v[208:211], v[2:5]
	v_mfma_f32_16x16x32_bf16 v[54:57], v[172:175], v[188:191], v[54:57]
	v_mfma_f32_16x16x32_bf16 v[50:53], v[180:183], v[188:191], v[50:53]
	v_mfma_f32_16x16x32_bf16 v[38:41], v[172:175], v[196:199], v[38:41]
	v_mfma_f32_16x16x32_bf16 v[34:37], v[180:183], v[196:199], v[34:37]
	v_mfma_f32_16x16x32_bf16 v[22:25], v[172:175], v[204:207], v[22:25]
	v_mfma_f32_16x16x32_bf16 v[18:21], v[180:183], v[204:207], v[18:21]
	v_mfma_f32_16x16x32_bf16 v[6:9], v[172:175], v[212:215], v[6:9]
	v_mfma_f32_16x16x32_bf16 v[2:5], v[180:183], v[212:215], v[2:5]
	s_barrier
	s_add_i32 s4, 0, 0x18000
	s_add_i32 s5, 0, 0x1c000
	v_add_u32_e32 v164, s4, v141
	v_add_u32_e32 v180, s5, v141
	ds_read_b128 v[144:147], v164
	ds_read_b128 v[156:159], v164 offset:1024
	ds_read_b128 v[160:163], v164 offset:2048
	ds_read_b128 v[164:167], v164 offset:3072
	ds_read_b128 v[168:171], v180
	ds_read_b128 v[172:175], v180 offset:1024
	ds_read_b128 v[176:179], v180 offset:2048
	ds_read_b128 v[180:183], v180 offset:3072
	s_add_u32 s2, vcc_lo, 0x40000
	s_addc_u32 s3, vcc_hi, 0
	s_mov_b32 m0, s72
	v_lshl_add_u64 v[218:219], s[2:3], 0, v[134:135]
	ds_read_b128 v[184:187], v143 offset:32768
	ds_read_b128 v[188:191], v143 offset:33792
	ds_read_b128 v[192:195], v143 offset:34816
	ds_read_b128 v[196:199], v143 offset:35840
	ds_read_b128 v[200:203], v143 offset:36864
	ds_read_b128 v[204:207], v143 offset:37888
	ds_read_b128 v[208:211], v143 offset:38912
	ds_read_b128 v[212:215], v143 offset:39936
	global_load_lds_dwordx4 v[218:219], off
	v_lshl_add_u64 v[218:219], s[2:3], 0, v[132:133]
	s_mov_b32 m0, s73
	s_nop 0
	global_load_lds_dwordx4 v[218:219], off
	s_waitcnt vmcnt(8)
	s_waitcnt lgkmcnt(0)
	s_barrier
	s_waitcnt lgkmcnt(0)
	v_mfma_f32_16x16x32_bf16 v[126:129], v[144:147], v[184:187], v[126:129]
	v_mfma_f32_16x16x32_bf16 v[122:125], v[160:163], v[184:187], v[122:125]
	v_mfma_f32_16x16x32_bf16 v[110:113], v[144:147], v[192:195], v[110:113]
	v_mfma_f32_16x16x32_bf16 v[106:109], v[160:163], v[192:195], v[106:109]
	v_mfma_f32_16x16x32_bf16 v[94:97], v[144:147], v[200:203], v[94:97]
	v_mfma_f32_16x16x32_bf16 v[90:93], v[160:163], v[200:203], v[90:93]
	v_mfma_f32_16x16x32_bf16 v[78:81], v[144:147], v[208:211], v[78:81]
	v_mfma_f32_16x16x32_bf16 v[74:77], v[160:163], v[208:211], v[74:77]
	v_mfma_f32_16x16x32_bf16 v[126:129], v[156:159], v[188:191], v[126:129]
	v_mfma_f32_16x16x32_bf16 v[122:125], v[164:167], v[188:191], v[122:125]
	v_mfma_f32_16x16x32_bf16 v[110:113], v[156:159], v[196:199], v[110:113]
	v_mfma_f32_16x16x32_bf16 v[106:109], v[164:167], v[196:199], v[106:109]
	v_mfma_f32_16x16x32_bf16 v[94:97], v[156:159], v[204:207], v[94:97]
	v_mfma_f32_16x16x32_bf16 v[90:93], v[164:167], v[204:207], v[90:93]
	v_mfma_f32_16x16x32_bf16 v[78:81], v[156:159], v[212:215], v[78:81]
	v_mfma_f32_16x16x32_bf16 v[74:77], v[164:167], v[212:215], v[74:77]
	v_mfma_f32_16x16x32_bf16 v[118:121], v[168:171], v[184:187], v[118:121]
	v_mfma_f32_16x16x32_bf16 v[114:117], v[176:179], v[184:187], v[114:117]
	v_mfma_f32_16x16x32_bf16 v[102:105], v[168:171], v[192:195], v[102:105]
	v_mfma_f32_16x16x32_bf16 v[98:101], v[176:179], v[192:195], v[98:101]
	v_mfma_f32_16x16x32_bf16 v[86:89], v[168:171], v[200:203], v[86:89]
	v_mfma_f32_16x16x32_bf16 v[82:85], v[176:179], v[200:203], v[82:85]
	v_mfma_f32_16x16x32_bf16 v[70:73], v[168:171], v[208:211], v[70:73]
	v_mfma_f32_16x16x32_bf16 v[66:69], v[176:179], v[208:211], v[66:69]
	v_mfma_f32_16x16x32_bf16 v[118:121], v[172:175], v[188:191], v[118:121]
	v_mfma_f32_16x16x32_bf16 v[114:117], v[180:183], v[188:191], v[114:117]
	v_mfma_f32_16x16x32_bf16 v[102:105], v[172:175], v[196:199], v[102:105]
	v_mfma_f32_16x16x32_bf16 v[98:101], v[180:183], v[196:199], v[98:101]
	v_mfma_f32_16x16x32_bf16 v[86:89], v[172:175], v[204:207], v[86:89]
	v_mfma_f32_16x16x32_bf16 v[82:85], v[180:183], v[204:207], v[82:85]
	v_mfma_f32_16x16x32_bf16 v[70:73], v[172:175], v[212:215], v[70:73]
	v_mfma_f32_16x16x32_bf16 v[66:69], v[180:183], v[212:215], v[66:69]
	s_barrier
	s_add_i32 s2, s4, s31
	v_lshl_add_u64 v[148:149], v[148:149], 0, s[74:75]
	s_mov_b32 m0, s2
	ds_read_b128 v[184:187], v143 offset:49152
	ds_read_b128 v[188:191], v143 offset:50176
	ds_read_b128 v[192:195], v143 offset:51200
	ds_read_b128 v[196:199], v143 offset:52224
	ds_read_b128 v[200:203], v143 offset:53248
	ds_read_b128 v[204:207], v143 offset:54272
	ds_read_b128 v[208:211], v143 offset:55296
	ds_read_b128 v[212:215], v143 offset:56320
	global_load_lds_dwordx4 v[148:149], off
	s_add_i32 m0, s2, 0x2000
	s_add_u32 s2, s26, 0x40080
	v_lshl_add_u64 v[148:149], v[152:153], 0, s[74:75]
	s_addc_u32 s3, s27, 0
	s_add_i32 s4, s5, s31
	global_load_lds_dwordx4 v[148:149], off
	v_lshl_add_u64 v[148:149], s[2:3], 0, v[0:1]
	s_mov_b32 m0, s4
	s_nop 0
	global_load_lds_dwordx4 v[148:149], off
	v_lshl_add_u64 v[148:149], s[2:3], 0, v[130:131]
	s_add_i32 m0, s4, 0x2000
	s_nop 0
	global_load_lds_dwordx4 v[148:149], off
	v_lshl_add_u64 v[148:149], v[154:155], 0, s[74:75]
	s_mov_b32 m0, s76
	s_nop 0
	global_load_lds_dwordx4 v[148:149], off
	v_lshl_add_u64 v[148:149], v[216:217], 0, s[74:75]
	s_mov_b32 m0, s77
	s_nop 0
	global_load_lds_dwordx4 v[148:149], off
	s_waitcnt vmcnt(8)
	s_waitcnt lgkmcnt(0)
	s_barrier
	s_waitcnt lgkmcnt(0)
	v_mfma_f32_16x16x32_bf16 v[62:65], v[144:147], v[184:187], v[62:65]
	v_mfma_f32_16x16x32_bf16 v[58:61], v[160:163], v[184:187], v[58:61]
	v_mfma_f32_16x16x32_bf16 v[46:49], v[144:147], v[192:195], v[46:49]
	v_mfma_f32_16x16x32_bf16 v[42:45], v[160:163], v[192:195], v[42:45]
	v_mfma_f32_16x16x32_bf16 v[30:33], v[144:147], v[200:203], v[30:33]
	v_mfma_f32_16x16x32_bf16 v[26:29], v[160:163], v[200:203], v[26:29]
	v_mfma_f32_16x16x32_bf16 v[14:17], v[144:147], v[208:211], v[14:17]
	v_mfma_f32_16x16x32_bf16 v[10:13], v[160:163], v[208:211], v[10:13]
	v_mfma_f32_16x16x32_bf16 v[62:65], v[156:159], v[188:191], v[62:65]
	v_mfma_f32_16x16x32_bf16 v[58:61], v[164:167], v[188:191], v[58:61]
	v_mfma_f32_16x16x32_bf16 v[46:49], v[156:159], v[196:199], v[46:49]
	v_mfma_f32_16x16x32_bf16 v[42:45], v[164:167], v[196:199], v[42:45]
	v_mfma_f32_16x16x32_bf16 v[30:33], v[156:159], v[204:207], v[30:33]
	v_mfma_f32_16x16x32_bf16 v[26:29], v[164:167], v[204:207], v[26:29]
	v_mfma_f32_16x16x32_bf16 v[14:17], v[156:159], v[212:215], v[14:17]
	v_mfma_f32_16x16x32_bf16 v[10:13], v[164:167], v[212:215], v[10:13]
	v_mfma_f32_16x16x32_bf16 v[54:57], v[168:171], v[184:187], v[54:57]
	v_mfma_f32_16x16x32_bf16 v[50:53], v[176:179], v[184:187], v[50:53]
	v_mfma_f32_16x16x32_bf16 v[38:41], v[168:171], v[192:195], v[38:41]
	v_mfma_f32_16x16x32_bf16 v[34:37], v[176:179], v[192:195], v[34:37]
	v_mfma_f32_16x16x32_bf16 v[22:25], v[168:171], v[200:203], v[22:25]
	v_mfma_f32_16x16x32_bf16 v[18:21], v[176:179], v[200:203], v[18:21]
	v_mfma_f32_16x16x32_bf16 v[6:9], v[168:171], v[208:211], v[6:9]
	v_mfma_f32_16x16x32_bf16 v[2:5], v[176:179], v[208:211], v[2:5]
	v_mfma_f32_16x16x32_bf16 v[54:57], v[172:175], v[188:191], v[54:57]
	v_mfma_f32_16x16x32_bf16 v[50:53], v[180:183], v[188:191], v[50:53]
	v_mfma_f32_16x16x32_bf16 v[38:41], v[172:175], v[196:199], v[38:41]
	v_mfma_f32_16x16x32_bf16 v[34:37], v[180:183], v[196:199], v[34:37]
	v_mfma_f32_16x16x32_bf16 v[22:25], v[172:175], v[204:207], v[22:25]
	v_mfma_f32_16x16x32_bf16 v[18:21], v[180:183], v[204:207], v[18:21]
	v_mfma_f32_16x16x32_bf16 v[6:9], v[172:175], v[212:215], v[6:9]
	v_mfma_f32_16x16x32_bf16 v[2:5], v[180:183], v[212:215], v[2:5]
	s_barrier
	s_add_i32 s33, s33, 2
	s_add_u32 s96, s96, 0x100
	s_addc_u32 s97, s97, 0
	s_add_u32 s83, s83, 0x100
	s_addc_u32 s71, s71, 0
	s_cmp_gt_u32 s33, 13
	s_cbranch_scc0 .LBB0_163
	s_and_b64 vcc, exec, s[34:35]
	s_cbranch_vccz .LBB0_166
	s_barrier

.LBB0_241:
	s_add_u32 s2, s96, 0xfffc0080
	s_addc_u32 s3, s97, -1
	s_add_i32 s70, 0, 0x10000
	s_cmp_eq_u32 s33, 12
	s_cselect_b32 vcc_hi, s49, s3
	s_cselect_b32 vcc_lo, s81, s2
	v_add_u32_e32 v148, s70, v141
	s_cselect_b32 s61, s47, s71
	s_cselect_b32 s60, s82, s83
	s_add_i32 s4, 0, 0x14000
	ds_read_b128 v[144:147], v148
	ds_read_b128 v[156:159], v148 offset:1024
	ds_read_b128 v[160:163], v148 offset:2048
	ds_read_b128 v[164:167], v148 offset:3072
	v_add_u32_e32 v148, s4, v141
	ds_read_b128 v[168:171], v148
	ds_read_b128 v[172:175], v148 offset:1024
	ds_read_b128 v[176:179], v148 offset:2048
	ds_read_b128 v[180:183], v148 offset:3072
	v_lshl_add_u64 v[216:217], s[96:97], 0, v[136:137]
	s_add_i32 m0, s38, 0xc000
	ds_read_b128 v[184:187], v143
	ds_read_b128 v[188:191], v143 offset:1024
	ds_read_b128 v[192:195], v143 offset:2048
	ds_read_b128 v[196:199], v143 offset:3072
	ds_read_b128 v[200:203], v143 offset:4096
	ds_read_b128 v[204:207], v143 offset:5120
	ds_read_b128 v[208:211], v143 offset:6144
	ds_read_b128 v[212:215], v143 offset:7168
	global_load_lds_dwordx4 v[216:217], off
	v_lshl_add_u64 v[216:217], s[96:97], 0, v[138:139]
	s_add_i32 m0, s38, 0xe000
	s_nop 0
	global_load_lds_dwordx4 v[216:217], off
	s_waitcnt vmcnt(8)
	s_waitcnt lgkmcnt(0)
	s_barrier
	s_waitcnt lgkmcnt(0)
	v_mfma_f32_16x16x32_bf16 v[126:129], v[144:147], v[184:187], v[126:129]
	v_mfma_f32_16x16x32_bf16 v[122:125], v[160:163], v[184:187], v[122:125]
	v_mfma_f32_16x16x32_bf16 v[118:121], v[144:147], v[192:195], v[118:121]
	v_mfma_f32_16x16x32_bf16 v[114:117], v[160:163], v[192:195], v[114:117]
	v_mfma_f32_16x16x32_bf16 v[102:105], v[144:147], v[200:203], v[102:105]
	v_mfma_f32_16x16x32_bf16 v[98:101], v[160:163], v[200:203], v[98:101]
	v_mfma_f32_16x16x32_bf16 v[86:89], v[144:147], v[208:211], v[86:89]
	v_mfma_f32_16x16x32_bf16 v[82:85], v[160:163], v[208:211], v[82:85]
	v_mfma_f32_16x16x32_bf16 v[126:129], v[156:159], v[188:191], v[126:129]
	v_mfma_f32_16x16x32_bf16 v[122:125], v[164:167], v[188:191], v[122:125]
	v_mfma_f32_16x16x32_bf16 v[118:121], v[156:159], v[196:199], v[118:121]
	v_mfma_f32_16x16x32_bf16 v[114:117], v[164:167], v[196:199], v[114:117]
	v_mfma_f32_16x16x32_bf16 v[102:105], v[156:159], v[204:207], v[102:105]
	v_mfma_f32_16x16x32_bf16 v[98:101], v[164:167], v[204:207], v[98:101]
	v_mfma_f32_16x16x32_bf16 v[86:89], v[156:159], v[212:215], v[86:89]
	v_mfma_f32_16x16x32_bf16 v[82:85], v[164:167], v[212:215], v[82:85]
	v_mfma_f32_16x16x32_bf16 v[110:113], v[168:171], v[184:187], v[110:113]
	v_mfma_f32_16x16x32_bf16 v[106:109], v[176:179], v[184:187], v[106:109]
	v_mfma_f32_16x16x32_bf16 v[94:97], v[168:171], v[192:195], v[94:97]
	v_mfma_f32_16x16x32_bf16 v[90:93], v[176:179], v[192:195], v[90:93]
	v_mfma_f32_16x16x32_bf16 v[78:81], v[168:171], v[200:203], v[78:81]
	v_mfma_f32_16x16x32_bf16 v[74:77], v[176:179], v[200:203], v[74:77]
	v_mfma_f32_16x16x32_bf16 v[70:73], v[168:171], v[208:211], v[70:73]
	v_mfma_f32_16x16x32_bf16 v[66:69], v[176:179], v[208:211], v[66:69]
	v_mfma_f32_16x16x32_bf16 v[110:113], v[172:175], v[188:191], v[110:113]
	v_mfma_f32_16x16x32_bf16 v[106:109], v[180:183], v[188:191], v[106:109]
	v_mfma_f32_16x16x32_bf16 v[94:97], v[172:175], v[196:199], v[94:97]
	v_mfma_f32_16x16x32_bf16 v[90:93], v[180:183], v[196:199], v[90:93]
	v_mfma_f32_16x16x32_bf16 v[78:81], v[172:175], v[204:207], v[78:81]
	v_mfma_f32_16x16x32_bf16 v[74:77], v[180:183], v[204:207], v[74:77]
	v_mfma_f32_16x16x32_bf16 v[70:73], v[172:175], v[212:215], v[70:73]
	v_mfma_f32_16x16x32_bf16 v[66:69], v[180:183], v[212:215], v[66:69]
	s_barrier
	s_add_i32 s2, s70, s37
	v_lshl_add_u64 v[216:217], s[60:61], 0, v[0:1]
	s_mov_b32 m0, s2
	ds_read_b128 v[184:187], v143 offset:16384
	ds_read_b128 v[188:191], v143 offset:17408
	ds_read_b128 v[192:195], v143 offset:18432
	ds_read_b128 v[196:199], v143 offset:19456
	ds_read_b128 v[200:203], v143 offset:20480
	ds_read_b128 v[204:207], v143 offset:21504
	ds_read_b128 v[208:211], v143 offset:22528
	ds_read_b128 v[212:215], v143 offset:23552
	global_load_lds_dwordx4 v[216:217], off
	s_add_i32 m0, s2, 0x2000
	s_add_u32 s2, s60, 0x40000
	v_lshl_add_u64 v[218:219], s[60:61], 0, v[134:135]
	s_addc_u32 s3, s61, 0
	s_add_i32 s4, s4, s37
	global_load_lds_dwordx4 v[218:219], off
	v_lshl_add_u64 v[220:221], s[2:3], 0, v[0:1]
	s_mov_b32 m0, s4
	v_lshl_add_u64 v[222:223], vcc, 0, v[132:133]
	global_load_lds_dwordx4 v[220:221], off
	v_lshl_add_u64 v[220:221], s[2:3], 0, v[134:135]
	s_add_i32 m0, s4, 0x2000
	s_nop 0
	global_load_lds_dwordx4 v[220:221], off
	v_lshl_add_u64 v[220:221], vcc, 0, v[130:131]
	s_mov_b32 m0, s38
	s_nop 0
	global_load_lds_dwordx4 v[220:221], off
	s_mov_b32 m0, s45
	s_nop 0
	global_load_lds_dwordx4 v[222:223], off
	s_waitcnt vmcnt(8)
	s_waitcnt lgkmcnt(0)
	s_barrier
	s_waitcnt lgkmcnt(0)
	v_mfma_f32_16x16x32_bf16 v[62:65], v[144:147], v[184:187], v[62:65]
	v_mfma_f32_16x16x32_bf16 v[58:61], v[160:163], v[184:187], v[58:61]
	v_mfma_f32_16x16x32_bf16 v[54:57], v[144:147], v[192:195], v[54:57]
	v_mfma_f32_16x16x32_bf16 v[50:53], v[160:163], v[192:195], v[50:53]
	v_mfma_f32_16x16x32_bf16 v[38:41], v[144:147], v[200:203], v[38:41]
	v_mfma_f32_16x16x32_bf16 v[34:37], v[160:163], v[200:203], v[34:37]
	v_mfma_f32_16x16x32_bf16 v[22:25], v[144:147], v[208:211], v[22:25]
	v_mfma_f32_16x16x32_bf16 v[18:21], v[160:163], v[208:211], v[18:21]
	v_mfma_f32_16x16x32_bf16 v[62:65], v[156:159], v[188:191], v[62:65]
	v_mfma_f32_16x16x32_bf16 v[58:61], v[164:167], v[188:191], v[58:61]
	v_mfma_f32_16x16x32_bf16 v[54:57], v[156:159], v[196:199], v[54:57]
	v_mfma_f32_16x16x32_bf16 v[50:53], v[164:167], v[196:199], v[50:53]
	v_mfma_f32_16x16x32_bf16 v[38:41], v[156:159], v[204:207], v[38:41]
	v_mfma_f32_16x16x32_bf16 v[34:37], v[164:167], v[204:207], v[34:37]
	v_mfma_f32_16x16x32_bf16 v[22:25], v[156:159], v[212:215], v[22:25]
	v_mfma_f32_16x16x32_bf16 v[18:21], v[164:167], v[212:215], v[18:21]
	v_mfma_f32_16x16x32_bf16 v[46:49], v[168:171], v[184:187], v[46:49]
	v_mfma_f32_16x16x32_bf16 v[42:45], v[176:179], v[184:187], v[42:45]
	v_mfma_f32_16x16x32_bf16 v[30:33], v[168:171], v[192:195], v[30:33]
	v_mfma_f32_16x16x32_bf16 v[26:29], v[176:179], v[192:195], v[26:29]
	v_mfma_f32_16x16x32_bf16 v[14:17], v[168:171], v[200:203], v[14:17]
	v_mfma_f32_16x16x32_bf16 v[10:13], v[176:179], v[200:203], v[10:13]
	v_mfma_f32_16x16x32_bf16 v[6:9], v[168:171], v[208:211], v[6:9]
	v_mfma_f32_16x16x32_bf16 v[2:5], v[176:179], v[208:211], v[2:5]
	v_mfma_f32_16x16x32_bf16 v[46:49], v[172:175], v[188:191], v[46:49]
	v_mfma_f32_16x16x32_bf16 v[42:45], v[180:183], v[188:191], v[42:45]
	v_mfma_f32_16x16x32_bf16 v[30:33], v[172:175], v[196:199], v[30:33]
	v_mfma_f32_16x16x32_bf16 v[26:29], v[180:183], v[196:199], v[26:29]
	v_mfma_f32_16x16x32_bf16 v[14:17], v[172:175], v[204:207], v[14:17]
	v_mfma_f32_16x16x32_bf16 v[10:13], v[180:183], v[204:207], v[10:13]
	v_mfma_f32_16x16x32_bf16 v[6:9], v[172:175], v[212:215], v[6:9]
	v_mfma_f32_16x16x32_bf16 v[2:5], v[180:183], v[212:215], v[2:5]
	s_barrier
	s_add_i32 s4, 0, 0x18000
	v_add_u32_e32 v148, s4, v141
	s_add_i32 s5, 0, 0x1c000
	ds_read_b128 v[144:147], v148
	ds_read_b128 v[156:159], v148 offset:1024
	ds_read_b128 v[160:163], v148 offset:2048
	ds_read_b128 v[164:167], v148 offset:3072
	v_add_u32_e32 v148, s5, v141
	ds_read_b128 v[168:171], v148
	ds_read_b128 v[172:175], v148 offset:1024
	ds_read_b128 v[176:179], v148 offset:2048
	ds_read_b128 v[180:183], v148 offset:3072
	s_add_u32 s2, vcc_lo, 0x40000
	s_addc_u32 s3, vcc_hi, 0
	s_mov_b32 m0, s72
	v_lshl_add_u64 v[224:225], s[2:3], 0, v[130:131]
	ds_read_b128 v[184:187], v143 offset:32768
	ds_read_b128 v[188:191], v143 offset:33792
	ds_read_b128 v[192:195], v143 offset:34816
	ds_read_b128 v[196:199], v143 offset:35840
	ds_read_b128 v[200:203], v143 offset:36864
	ds_read_b128 v[204:207], v143 offset:37888
	ds_read_b128 v[208:211], v143 offset:38912
	ds_read_b128 v[212:215], v143 offset:39936
	global_load_lds_dwordx4 v[224:225], off
	v_lshl_add_u64 v[224:225], s[2:3], 0, v[132:133]
	s_mov_b32 m0, s73
	s_nop 0
	global_load_lds_dwordx4 v[224:225], off
	s_waitcnt vmcnt(8)
	s_waitcnt lgkmcnt(0)
	s_barrier
	s_waitcnt lgkmcnt(0)
	v_mfma_f32_16x16x32_bf16 v[126:129], v[144:147], v[184:187], v[126:129]
	v_mfma_f32_16x16x32_bf16 v[122:125], v[160:163], v[184:187], v[122:125]
	v_mfma_f32_16x16x32_bf16 v[118:121], v[144:147], v[192:195], v[118:121]
	v_mfma_f32_16x16x32_bf16 v[114:117], v[160:163], v[192:195], v[114:117]
	v_mfma_f32_16x16x32_bf16 v[102:105], v[144:147], v[200:203], v[102:105]
	v_mfma_f32_16x16x32_bf16 v[98:101], v[160:163], v[200:203], v[98:101]
	v_mfma_f32_16x16x32_bf16 v[86:89], v[144:147], v[208:211], v[86:89]
	v_mfma_f32_16x16x32_bf16 v[82:85], v[160:163], v[208:211], v[82:85]
	v_mfma_f32_16x16x32_bf16 v[126:129], v[156:159], v[188:191], v[126:129]
	v_mfma_f32_16x16x32_bf16 v[122:125], v[164:167], v[188:191], v[122:125]
	v_mfma_f32_16x16x32_bf16 v[118:121], v[156:159], v[196:199], v[118:121]
	v_mfma_f32_16x16x32_bf16 v[114:117], v[164:167], v[196:199], v[114:117]
	v_mfma_f32_16x16x32_bf16 v[102:105], v[156:159], v[204:207], v[102:105]
	v_mfma_f32_16x16x32_bf16 v[98:101], v[164:167], v[204:207], v[98:101]
	v_mfma_f32_16x16x32_bf16 v[86:89], v[156:159], v[212:215], v[86:89]
	v_mfma_f32_16x16x32_bf16 v[82:85], v[164:167], v[212:215], v[82:85]
	v_mfma_f32_16x16x32_bf16 v[110:113], v[168:171], v[184:187], v[110:113]
	v_mfma_f32_16x16x32_bf16 v[106:109], v[176:179], v[184:187], v[106:109]
	v_mfma_f32_16x16x32_bf16 v[94:97], v[168:171], v[192:195], v[94:97]
	v_mfma_f32_16x16x32_bf16 v[90:93], v[176:179], v[192:195], v[90:93]
	v_mfma_f32_16x16x32_bf16 v[78:81], v[168:171], v[200:203], v[78:81]
	v_mfma_f32_16x16x32_bf16 v[74:77], v[176:179], v[200:203], v[74:77]
	v_mfma_f32_16x16x32_bf16 v[70:73], v[168:171], v[208:211], v[70:73]
	v_mfma_f32_16x16x32_bf16 v[66:69], v[176:179], v[208:211], v[66:69]
	v_mfma_f32_16x16x32_bf16 v[110:113], v[172:175], v[188:191], v[110:113]
	v_mfma_f32_16x16x32_bf16 v[106:109], v[180:183], v[188:191], v[106:109]
	v_mfma_f32_16x16x32_bf16 v[94:97], v[172:175], v[196:199], v[94:97]
	v_mfma_f32_16x16x32_bf16 v[90:93], v[180:183], v[196:199], v[90:93]
	v_mfma_f32_16x16x32_bf16 v[78:81], v[172:175], v[204:207], v[78:81]
	v_mfma_f32_16x16x32_bf16 v[74:77], v[180:183], v[204:207], v[74:77]
	v_mfma_f32_16x16x32_bf16 v[70:73], v[172:175], v[212:215], v[70:73]
	v_mfma_f32_16x16x32_bf16 v[66:69], v[180:183], v[212:215], v[66:69]
	s_barrier
	s_add_i32 s2, s4, s37
	v_lshl_add_u64 v[216:217], v[216:217], 0, s[74:75]
	s_mov_b32 m0, s2
	ds_read_b128 v[184:187], v143 offset:49152
	ds_read_b128 v[188:191], v143 offset:50176
	ds_read_b128 v[192:195], v143 offset:51200
	ds_read_b128 v[196:199], v143 offset:52224
	ds_read_b128 v[200:203], v143 offset:53248
	ds_read_b128 v[204:207], v143 offset:54272
	ds_read_b128 v[208:211], v143 offset:55296
	ds_read_b128 v[212:215], v143 offset:56320
	global_load_lds_dwordx4 v[216:217], off
	s_add_i32 m0, s2, 0x2000
	s_add_u32 s2, s60, 0x40080
	v_lshl_add_u64 v[216:217], v[218:219], 0, s[74:75]
	s_addc_u32 s3, s61, 0
	s_add_i32 s4, s5, s37
	global_load_lds_dwordx4 v[216:217], off
	v_lshl_add_u64 v[216:217], s[2:3], 0, v[0:1]
	s_mov_b32 m0, s4
	s_nop 0
	global_load_lds_dwordx4 v[216:217], off
	v_lshl_add_u64 v[216:217], s[2:3], 0, v[134:135]
	s_add_i32 m0, s4, 0x2000
	s_nop 0
	global_load_lds_dwordx4 v[216:217], off
	v_lshl_add_u64 v[216:217], v[220:221], 0, s[74:75]
	s_mov_b32 m0, s76
	s_nop 0
	global_load_lds_dwordx4 v[216:217], off
	v_lshl_add_u64 v[216:217], v[222:223], 0, s[74:75]
	s_mov_b32 m0, s77
	s_nop 0
	global_load_lds_dwordx4 v[216:217], off
	s_waitcnt vmcnt(8)
	s_waitcnt lgkmcnt(0)
	s_barrier
	s_waitcnt lgkmcnt(0)
	v_mfma_f32_16x16x32_bf16 v[62:65], v[144:147], v[184:187], v[62:65]
	v_mfma_f32_16x16x32_bf16 v[58:61], v[160:163], v[184:187], v[58:61]
	v_mfma_f32_16x16x32_bf16 v[54:57], v[144:147], v[192:195], v[54:57]
	v_mfma_f32_16x16x32_bf16 v[50:53], v[160:163], v[192:195], v[50:53]
	v_mfma_f32_16x16x32_bf16 v[38:41], v[144:147], v[200:203], v[38:41]
	v_mfma_f32_16x16x32_bf16 v[34:37], v[160:163], v[200:203], v[34:37]
	v_mfma_f32_16x16x32_bf16 v[22:25], v[144:147], v[208:211], v[22:25]
	v_mfma_f32_16x16x32_bf16 v[18:21], v[160:163], v[208:211], v[18:21]
	v_mfma_f32_16x16x32_bf16 v[62:65], v[156:159], v[188:191], v[62:65]
	v_mfma_f32_16x16x32_bf16 v[58:61], v[164:167], v[188:191], v[58:61]
	v_mfma_f32_16x16x32_bf16 v[54:57], v[156:159], v[196:199], v[54:57]
	v_mfma_f32_16x16x32_bf16 v[50:53], v[164:167], v[196:199], v[50:53]
	v_mfma_f32_16x16x32_bf16 v[38:41], v[156:159], v[204:207], v[38:41]
	v_mfma_f32_16x16x32_bf16 v[34:37], v[164:167], v[204:207], v[34:37]
	v_mfma_f32_16x16x32_bf16 v[22:25], v[156:159], v[212:215], v[22:25]
	v_mfma_f32_16x16x32_bf16 v[18:21], v[164:167], v[212:215], v[18:21]
	v_mfma_f32_16x16x32_bf16 v[46:49], v[168:171], v[184:187], v[46:49]
	v_mfma_f32_16x16x32_bf16 v[42:45], v[176:179], v[184:187], v[42:45]
	v_mfma_f32_16x16x32_bf16 v[30:33], v[168:171], v[192:195], v[30:33]
	v_mfma_f32_16x16x32_bf16 v[26:29], v[176:179], v[192:195], v[26:29]
	v_mfma_f32_16x16x32_bf16 v[14:17], v[168:171], v[200:203], v[14:17]
	v_mfma_f32_16x16x32_bf16 v[10:13], v[176:179], v[200:203], v[10:13]
	v_mfma_f32_16x16x32_bf16 v[6:9], v[168:171], v[208:211], v[6:9]
	v_mfma_f32_16x16x32_bf16 v[2:5], v[176:179], v[208:211], v[2:5]
	v_mfma_f32_16x16x32_bf16 v[46:49], v[172:175], v[188:191], v[46:49]
	v_mfma_f32_16x16x32_bf16 v[42:45], v[180:183], v[188:191], v[42:45]
	v_mfma_f32_16x16x32_bf16 v[30:33], v[172:175], v[196:199], v[30:33]
	v_mfma_f32_16x16x32_bf16 v[26:29], v[180:183], v[196:199], v[26:29]
	v_mfma_f32_16x16x32_bf16 v[14:17], v[172:175], v[204:207], v[14:17]
	v_mfma_f32_16x16x32_bf16 v[10:13], v[180:183], v[204:207], v[10:13]
	v_mfma_f32_16x16x32_bf16 v[6:9], v[172:175], v[212:215], v[6:9]
	v_mfma_f32_16x16x32_bf16 v[2:5], v[180:183], v[212:215], v[2:5]
	s_barrier
	s_add_i32 s33, s33, 2
	s_add_u32 s96, s96, 0x100
	s_addc_u32 s97, s97, 0
	s_add_u32 s83, s83, 0x100
	s_addc_u32 s71, s71, 0
	s_cmp_gt_u32 s33, 13
	s_cbranch_scc0 .LBB0_241
	s_and_b64 vcc, exec, s[34:35]
	s_mov_b64 s[82:83], s[90:91]
	s_cbranch_vccz .LBB0_244
	s_barrier

.LBB0_253:
	s_add_i32 s4, s26, 0x100
	s_and_b64 s[2:3], s[46:47], exec
	s_cselect_b32 s3, 0, s4
	s_cselect_b32 s2, 0, 0
	s_add_u32 s48, s34, s3
	s_addc_u32 s49, s35, s2
	s_add_i32 s4, 0, 0x10000
	s_add_u32 s50, s24, s3
	s_addc_u32 s51, s25, s2
	s_add_i32 s2, 0, 0x14000
	s_add_u32 s96, s42, s26
	s_addc_u32 s97, s43, 0
	s_add_i32 vcc_hi, s4, s73
	s_add_i32 m0, s76, 0xc000
	s_add_i32 s3, s76, 0xe000
	s_add_i32 s38, vcc_hi, 0x2000
	v_add_u32_e32 v148, s4, v138
	s_add_u32 s60, s50, 0x40000
	ds_read_b128 v[140:143], v148
	ds_read_b128 v[144:147], v148 offset:1024
	ds_read_b128 v[156:159], v148 offset:2048
	ds_read_b128 v[160:163], v148 offset:3072
	v_add_u32_e32 v148, s2, v138
	s_addc_u32 s61, s51, 0
	s_add_i32 s31, s2, s73
	ds_read_b128 v[164:167], v148
	ds_read_b128 v[168:171], v148 offset:1024
	ds_read_b128 v[172:175], v148 offset:2048
	ds_read_b128 v[176:179], v148 offset:3072
	s_add_i32 s37, s31, 0x2000
	s_add_i32 vcc_lo, 0, 0x18000
	s_add_i32 s83, 0, 0x1c000
	s_add_u32 s46, s48, 0x40000
	s_addc_u32 s47, s49, 0
	s_add_i32 s71, vcc_lo, s73
	s_add_i32 s33, s71, 0x2000
	s_add_u32 s26, s50, 0x40080
	s_addc_u32 s27, s51, 0
	s_add_i32 s80, s83, s73
	s_add_i32 s72, s80, 0x2000
	v_lshl_add_u64 v[212:213], s[96:97], 0, v[134:135]
	v_lshl_add_u64 v[212:213], v[212:213], 0, s[74:75]
	ds_read_b128 v[180:183], v139
	ds_read_b128 v[184:187], v139 offset:1024
	ds_read_b128 v[188:191], v139 offset:2048
	ds_read_b128 v[192:195], v139 offset:3072
	ds_read_b128 v[196:199], v139 offset:4096
	ds_read_b128 v[200:203], v139 offset:5120
	ds_read_b128 v[204:207], v139 offset:6144
	ds_read_b128 v[208:211], v139 offset:7168
	global_load_lds_dwordx4 v[212:213], off
	v_lshl_add_u64 v[212:213], s[96:97], 0, v[132:133]
	v_lshl_add_u64 v[212:213], v[212:213], 0, s[74:75]
	s_mov_b32 m0, s3
	s_nop 0
	global_load_lds_dwordx4 v[212:213], off
	s_waitcnt vmcnt(8)
	s_waitcnt lgkmcnt(0)
	s_barrier
	s_waitcnt lgkmcnt(0)
	v_mfma_f32_16x16x32_bf16 v[126:129], v[140:143], v[180:183], v[126:129]
	v_mfma_f32_16x16x32_bf16 v[122:125], v[156:159], v[180:183], v[122:125]
	v_mfma_f32_16x16x32_bf16 v[118:121], v[140:143], v[188:191], v[118:121]
	v_mfma_f32_16x16x32_bf16 v[114:117], v[156:159], v[188:191], v[114:117]
	v_mfma_f32_16x16x32_bf16 v[106:109], v[140:143], v[196:199], v[106:109]
	v_mfma_f32_16x16x32_bf16 v[98:101], v[156:159], v[196:199], v[98:101]
	v_mfma_f32_16x16x32_bf16 v[90:93], v[140:143], v[204:207], v[90:93]
	v_mfma_f32_16x16x32_bf16 v[82:85], v[156:159], v[204:207], v[82:85]
	v_mfma_f32_16x16x32_bf16 v[126:129], v[144:147], v[184:187], v[126:129]
	v_mfma_f32_16x16x32_bf16 v[122:125], v[160:163], v[184:187], v[122:125]
	v_mfma_f32_16x16x32_bf16 v[118:121], v[144:147], v[192:195], v[118:121]
	v_mfma_f32_16x16x32_bf16 v[114:117], v[160:163], v[192:195], v[114:117]
	v_mfma_f32_16x16x32_bf16 v[106:109], v[144:147], v[200:203], v[106:109]
	v_mfma_f32_16x16x32_bf16 v[98:101], v[160:163], v[200:203], v[98:101]
	v_mfma_f32_16x16x32_bf16 v[90:93], v[144:147], v[208:211], v[90:93]
	v_mfma_f32_16x16x32_bf16 v[82:85], v[160:163], v[208:211], v[82:85]
	v_mfma_f32_16x16x32_bf16 v[110:113], v[164:167], v[180:183], v[110:113]
	v_mfma_f32_16x16x32_bf16 v[102:105], v[172:175], v[180:183], v[102:105]
	v_mfma_f32_16x16x32_bf16 v[94:97], v[164:167], v[188:191], v[94:97]
	v_mfma_f32_16x16x32_bf16 v[86:89], v[172:175], v[188:191], v[86:89]
	v_mfma_f32_16x16x32_bf16 v[78:81], v[164:167], v[196:199], v[78:81]
	v_mfma_f32_16x16x32_bf16 v[74:77], v[172:175], v[196:199], v[74:77]
	v_mfma_f32_16x16x32_bf16 v[70:73], v[164:167], v[204:207], v[70:73]
	v_mfma_f32_16x16x32_bf16 v[66:69], v[172:175], v[204:207], v[66:69]
	v_mfma_f32_16x16x32_bf16 v[110:113], v[168:171], v[184:187], v[110:113]
	v_mfma_f32_16x16x32_bf16 v[102:105], v[176:179], v[184:187], v[102:105]
	v_mfma_f32_16x16x32_bf16 v[94:97], v[168:171], v[192:195], v[94:97]
	v_mfma_f32_16x16x32_bf16 v[86:89], v[176:179], v[192:195], v[86:89]
	v_mfma_f32_16x16x32_bf16 v[78:81], v[168:171], v[200:203], v[78:81]
	v_mfma_f32_16x16x32_bf16 v[74:77], v[176:179], v[200:203], v[74:77]
	v_mfma_f32_16x16x32_bf16 v[70:73], v[168:171], v[208:211], v[70:73]
	v_mfma_f32_16x16x32_bf16 v[66:69], v[176:179], v[208:211], v[66:69]
	s_barrier
	s_mov_b32 m0, vcc_hi
	v_lshl_add_u64 v[212:213], s[50:51], 0, v[0:1]
	ds_read_b128 v[180:183], v139 offset:16384
	ds_read_b128 v[184:187], v139 offset:17408
	ds_read_b128 v[188:191], v139 offset:18432
	ds_read_b128 v[192:195], v139 offset:19456
	ds_read_b128 v[196:199], v139 offset:20480
	ds_read_b128 v[200:203], v139 offset:21504
	ds_read_b128 v[204:207], v139 offset:22528
	ds_read_b128 v[208:211], v139 offset:23552
	global_load_lds_dwordx4 v[212:213], off
	v_lshl_add_u64 v[214:215], s[50:51], 0, v[130:131]
	s_mov_b32 m0, s38
	v_lshl_add_u64 v[216:217], s[60:61], 0, v[0:1]
	global_load_lds_dwordx4 v[214:215], off
	s_mov_b32 m0, s31
	v_lshl_add_u64 v[218:219], s[48:49], 0, v[132:133]
	global_load_lds_dwordx4 v[216:217], off
	v_lshl_add_u64 v[216:217], s[60:61], 0, v[130:131]
	s_mov_b32 m0, s37
	s_nop 0
	global_load_lds_dwordx4 v[216:217], off
	v_lshl_add_u64 v[216:217], s[48:49], 0, v[134:135]
	s_mov_b32 m0, s76
	s_nop 0
	global_load_lds_dwordx4 v[216:217], off
	s_mov_b32 m0, s77
	s_nop 0
	global_load_lds_dwordx4 v[218:219], off
	s_waitcnt vmcnt(8)
	s_waitcnt lgkmcnt(0)
	s_barrier
	s_waitcnt lgkmcnt(0)
	v_mfma_f32_16x16x32_bf16 v[62:65], v[140:143], v[180:183], v[62:65]
	v_mfma_f32_16x16x32_bf16 v[58:61], v[156:159], v[180:183], v[58:61]
	v_mfma_f32_16x16x32_bf16 v[54:57], v[140:143], v[188:191], v[54:57]
	v_mfma_f32_16x16x32_bf16 v[50:53], v[156:159], v[188:191], v[50:53]
	v_mfma_f32_16x16x32_bf16 v[38:41], v[140:143], v[196:199], v[38:41]
	v_mfma_f32_16x16x32_bf16 v[34:37], v[156:159], v[196:199], v[34:37]
	v_mfma_f32_16x16x32_bf16 v[22:25], v[140:143], v[204:207], v[22:25]
	v_mfma_f32_16x16x32_bf16 v[18:21], v[156:159], v[204:207], v[18:21]
	v_mfma_f32_16x16x32_bf16 v[62:65], v[144:147], v[184:187], v[62:65]
	v_mfma_f32_16x16x32_bf16 v[58:61], v[160:163], v[184:187], v[58:61]
	v_mfma_f32_16x16x32_bf16 v[54:57], v[144:147], v[192:195], v[54:57]
	v_mfma_f32_16x16x32_bf16 v[50:53], v[160:163], v[192:195], v[50:53]
	v_mfma_f32_16x16x32_bf16 v[38:41], v[144:147], v[200:203], v[38:41]
	v_mfma_f32_16x16x32_bf16 v[34:37], v[160:163], v[200:203], v[34:37]
	v_mfma_f32_16x16x32_bf16 v[22:25], v[144:147], v[208:211], v[22:25]
	v_mfma_f32_16x16x32_bf16 v[18:21], v[160:163], v[208:211], v[18:21]
	v_mfma_f32_16x16x32_bf16 v[46:49], v[164:167], v[180:183], v[46:49]
	v_mfma_f32_16x16x32_bf16 v[42:45], v[172:175], v[180:183], v[42:45]
	v_mfma_f32_16x16x32_bf16 v[30:33], v[164:167], v[188:191], v[30:33]
	v_mfma_f32_16x16x32_bf16 v[26:29], v[172:175], v[188:191], v[26:29]
	v_mfma_f32_16x16x32_bf16 v[14:17], v[164:167], v[196:199], v[14:17]
	v_mfma_f32_16x16x32_bf16 v[10:13], v[172:175], v[196:199], v[10:13]
	v_mfma_f32_16x16x32_bf16 v[6:9], v[164:167], v[204:207], v[6:9]
	v_mfma_f32_16x16x32_bf16 v[2:5], v[172:175], v[204:207], v[2:5]
	v_mfma_f32_16x16x32_bf16 v[46:49], v[168:171], v[184:187], v[46:49]
	v_mfma_f32_16x16x32_bf16 v[42:45], v[176:179], v[184:187], v[42:45]
	v_mfma_f32_16x16x32_bf16 v[30:33], v[168:171], v[192:195], v[30:33]
	v_mfma_f32_16x16x32_bf16 v[26:29], v[176:179], v[192:195], v[26:29]
	v_mfma_f32_16x16x32_bf16 v[14:17], v[168:171], v[200:203], v[14:17]
	v_mfma_f32_16x16x32_bf16 v[10:13], v[176:179], v[200:203], v[10:13]
	v_mfma_f32_16x16x32_bf16 v[6:9], v[168:171], v[208:211], v[6:9]
	v_mfma_f32_16x16x32_bf16 v[2:5], v[176:179], v[208:211], v[2:5]
	s_barrier
	v_add_u32_e32 v148, vcc_lo, v138
	ds_read_b128 v[140:143], v148
	ds_read_b128 v[144:147], v148 offset:1024
	ds_read_b128 v[156:159], v148 offset:2048
	ds_read_b128 v[160:163], v148 offset:3072
	v_add_u32_e32 v148, s83, v138
	ds_read_b128 v[164:167], v148
	ds_read_b128 v[168:171], v148 offset:1024
	ds_read_b128 v[172:175], v148 offset:2048
	ds_read_b128 v[176:179], v148 offset:3072
	s_mov_b32 m0, s78
	v_lshl_add_u64 v[220:221], s[46:47], 0, v[134:135]
	ds_read_b128 v[180:183], v139 offset:32768
	ds_read_b128 v[184:187], v139 offset:33792
	ds_read_b128 v[188:191], v139 offset:34816
	ds_read_b128 v[192:195], v139 offset:35840
	ds_read_b128 v[196:199], v139 offset:36864
	ds_read_b128 v[200:203], v139 offset:37888
	ds_read_b128 v[204:207], v139 offset:38912
	ds_read_b128 v[208:211], v139 offset:39936
	global_load_lds_dwordx4 v[220:221], off
	v_lshl_add_u64 v[220:221], s[46:47], 0, v[132:133]
	s_mov_b32 m0, s79
	s_nop 0
	global_load_lds_dwordx4 v[220:221], off
	s_waitcnt vmcnt(8)
	s_waitcnt lgkmcnt(0)
	s_barrier
	s_waitcnt lgkmcnt(0)
	v_mfma_f32_16x16x32_bf16 v[126:129], v[140:143], v[180:183], v[126:129]
	v_mfma_f32_16x16x32_bf16 v[122:125], v[156:159], v[180:183], v[122:125]
	v_mfma_f32_16x16x32_bf16 v[118:121], v[140:143], v[188:191], v[118:121]
	v_mfma_f32_16x16x32_bf16 v[114:117], v[156:159], v[188:191], v[114:117]
	v_mfma_f32_16x16x32_bf16 v[106:109], v[140:143], v[196:199], v[106:109]
	v_mfma_f32_16x16x32_bf16 v[98:101], v[156:159], v[196:199], v[98:101]
	v_mfma_f32_16x16x32_bf16 v[90:93], v[140:143], v[204:207], v[90:93]
	v_mfma_f32_16x16x32_bf16 v[82:85], v[156:159], v[204:207], v[82:85]
	v_mfma_f32_16x16x32_bf16 v[126:129], v[144:147], v[184:187], v[126:129]
	v_mfma_f32_16x16x32_bf16 v[122:125], v[160:163], v[184:187], v[122:125]
	v_mfma_f32_16x16x32_bf16 v[118:121], v[144:147], v[192:195], v[118:121]
	v_mfma_f32_16x16x32_bf16 v[114:117], v[160:163], v[192:195], v[114:117]
	v_mfma_f32_16x16x32_bf16 v[106:109], v[144:147], v[200:203], v[106:109]
	v_mfma_f32_16x16x32_bf16 v[98:101], v[160:163], v[200:203], v[98:101]
	v_mfma_f32_16x16x32_bf16 v[90:93], v[144:147], v[208:211], v[90:93]
	v_mfma_f32_16x16x32_bf16 v[82:85], v[160:163], v[208:211], v[82:85]
	v_mfma_f32_16x16x32_bf16 v[110:113], v[164:167], v[180:183], v[110:113]
	v_mfma_f32_16x16x32_bf16 v[102:105], v[172:175], v[180:183], v[102:105]
	v_mfma_f32_16x16x32_bf16 v[94:97], v[164:167], v[188:191], v[94:97]
	v_mfma_f32_16x16x32_bf16 v[86:89], v[172:175], v[188:191], v[86:89]
	v_mfma_f32_16x16x32_bf16 v[78:81], v[164:167], v[196:199], v[78:81]
	v_mfma_f32_16x16x32_bf16 v[74:77], v[172:175], v[196:199], v[74:77]
	v_mfma_f32_16x16x32_bf16 v[70:73], v[164:167], v[204:207], v[70:73]
	v_mfma_f32_16x16x32_bf16 v[66:69], v[172:175], v[204:207], v[66:69]
	v_mfma_f32_16x16x32_bf16 v[110:113], v[168:171], v[184:187], v[110:113]
	v_mfma_f32_16x16x32_bf16 v[102:105], v[176:179], v[184:187], v[102:105]
	v_mfma_f32_16x16x32_bf16 v[94:97], v[168:171], v[192:195], v[94:97]
	v_mfma_f32_16x16x32_bf16 v[86:89], v[176:179], v[192:195], v[86:89]
	v_mfma_f32_16x16x32_bf16 v[78:81], v[168:171], v[200:203], v[78:81]
	v_mfma_f32_16x16x32_bf16 v[74:77], v[176:179], v[200:203], v[74:77]
	v_mfma_f32_16x16x32_bf16 v[70:73], v[168:171], v[208:211], v[70:73]
	v_mfma_f32_16x16x32_bf16 v[66:69], v[176:179], v[208:211], v[66:69]
	s_barrier
	s_mov_b32 m0, s71
	v_lshl_add_u64 v[212:213], v[212:213], 0, s[74:75]
	ds_read_b128 v[180:183], v139 offset:49152
	ds_read_b128 v[184:187], v139 offset:50176
	ds_read_b128 v[188:191], v139 offset:51200
	ds_read_b128 v[192:195], v139 offset:52224
	ds_read_b128 v[196:199], v139 offset:53248
	ds_read_b128 v[200:203], v139 offset:54272
	ds_read_b128 v[204:207], v139 offset:55296
	ds_read_b128 v[208:211], v139 offset:56320
	global_load_lds_dwordx4 v[212:213], off
	v_lshl_add_u64 v[212:213], v[214:215], 0, s[74:75]
	s_mov_b32 m0, s33
	s_nop 0
	global_load_lds_dwordx4 v[212:213], off
	v_lshl_add_u64 v[212:213], s[26:27], 0, v[0:1]
	s_mov_b32 m0, s80
	s_nop 0
	global_load_lds_dwordx4 v[212:213], off
	v_lshl_add_u64 v[212:213], s[26:27], 0, v[130:131]
	s_mov_b32 m0, s72
	s_nop 0
	global_load_lds_dwordx4 v[212:213], off
	v_lshl_add_u64 v[212:213], v[216:217], 0, s[74:75]
	s_mov_b32 m0, s81
	s_nop 0
	global_load_lds_dwordx4 v[212:213], off
	v_lshl_add_u64 v[212:213], v[218:219], 0, s[74:75]
	s_mov_b32 m0, s82
	s_nop 0
	global_load_lds_dwordx4 v[212:213], off
	s_waitcnt vmcnt(8)
	s_waitcnt lgkmcnt(0)
	s_barrier
	s_waitcnt lgkmcnt(0)
	v_mfma_f32_16x16x32_bf16 v[62:65], v[140:143], v[180:183], v[62:65]
	v_mfma_f32_16x16x32_bf16 v[58:61], v[156:159], v[180:183], v[58:61]
	v_mfma_f32_16x16x32_bf16 v[54:57], v[140:143], v[188:191], v[54:57]
	v_mfma_f32_16x16x32_bf16 v[50:53], v[156:159], v[188:191], v[50:53]
	v_mfma_f32_16x16x32_bf16 v[38:41], v[140:143], v[196:199], v[38:41]
	v_mfma_f32_16x16x32_bf16 v[34:37], v[156:159], v[196:199], v[34:37]
	v_mfma_f32_16x16x32_bf16 v[22:25], v[140:143], v[204:207], v[22:25]
	v_mfma_f32_16x16x32_bf16 v[18:21], v[156:159], v[204:207], v[18:21]
	v_mfma_f32_16x16x32_bf16 v[62:65], v[144:147], v[184:187], v[62:65]
	v_mfma_f32_16x16x32_bf16 v[58:61], v[160:163], v[184:187], v[58:61]
	v_mfma_f32_16x16x32_bf16 v[54:57], v[144:147], v[192:195], v[54:57]
	v_mfma_f32_16x16x32_bf16 v[50:53], v[160:163], v[192:195], v[50:53]
	v_mfma_f32_16x16x32_bf16 v[38:41], v[144:147], v[200:203], v[38:41]
	v_mfma_f32_16x16x32_bf16 v[34:37], v[160:163], v[200:203], v[34:37]
	v_mfma_f32_16x16x32_bf16 v[22:25], v[144:147], v[208:211], v[22:25]
	v_mfma_f32_16x16x32_bf16 v[18:21], v[160:163], v[208:211], v[18:21]
	v_mfma_f32_16x16x32_bf16 v[46:49], v[164:167], v[180:183], v[46:49]
	v_mfma_f32_16x16x32_bf16 v[42:45], v[172:175], v[180:183], v[42:45]
	v_mfma_f32_16x16x32_bf16 v[30:33], v[164:167], v[188:191], v[30:33]
	v_mfma_f32_16x16x32_bf16 v[26:29], v[172:175], v[188:191], v[26:29]
	v_mfma_f32_16x16x32_bf16 v[14:17], v[164:167], v[196:199], v[14:17]
	v_mfma_f32_16x16x32_bf16 v[10:13], v[172:175], v[196:199], v[10:13]
	v_mfma_f32_16x16x32_bf16 v[6:9], v[164:167], v[204:207], v[6:9]
	v_mfma_f32_16x16x32_bf16 v[2:5], v[172:175], v[204:207], v[2:5]
	v_mfma_f32_16x16x32_bf16 v[46:49], v[168:171], v[184:187], v[46:49]
	v_mfma_f32_16x16x32_bf16 v[42:45], v[176:179], v[184:187], v[42:45]
	v_mfma_f32_16x16x32_bf16 v[30:33], v[168:171], v[192:195], v[30:33]
	v_mfma_f32_16x16x32_bf16 v[26:29], v[176:179], v[192:195], v[26:29]
	v_mfma_f32_16x16x32_bf16 v[14:17], v[168:171], v[200:203], v[14:17]
	v_mfma_f32_16x16x32_bf16 v[10:13], v[176:179], v[200:203], v[10:13]
	v_mfma_f32_16x16x32_bf16 v[6:9], v[168:171], v[208:211], v[6:9]
	v_mfma_f32_16x16x32_bf16 v[2:5], v[176:179], v[208:211], v[2:5]
	s_barrier
	s_andn2_b64 vcc, exec, s[44:45]
	s_mov_b64 s[46:47], -1
	s_mov_b64 s[44:45], 0
	s_movk_i32 s26, 0x100
	s_cbranch_vccz .LBB0_253
	s_cmpk_lt_u32 s11, 0x100
	v_readlane_b32 s70, v250, 13
	s_mov_b64 s[82:83], s[90:91]
	v_readlane_b32 s71, v250, 14
	s_cbranch_scc0 .LBB0_256
	s_barrier

.LBB0_1962:
	s_add_u32 s2, vcc_lo, 0xfffc0080
	s_addc_u32 s3, vcc_hi, -1
	s_add_i32 s33, 0, 0x10000
	s_cmp_eq_u32 s71, 12
	s_cselect_b32 s61, s45, s3
	s_cselect_b32 s60, s47, s2
	v_add_u32_e32 v0, s33, v147
	s_cselect_b32 s27, s49, s82
	s_cselect_b32 s26, s51, s81
	s_add_i32 s2, 0, 0x14000
	ds_read_b128 v[142:145], v0
	ds_read_b128 v[158:161], v0 offset:1024
	ds_read_b128 v[162:165], v0 offset:2048
	ds_read_b128 v[166:169], v0 offset:3072
	v_add_u32_e32 v0, s2, v147
	ds_read_b128 v[170:173], v0
	ds_read_b128 v[174:177], v0 offset:1024
	ds_read_b128 v[178:181], v0 offset:2048
	ds_read_b128 v[182:185], v0 offset:3072
	v_lshl_add_u64 v[218:219], vcc, 0, v[138:139]
	s_add_i32 m0, s37, 0xc000
	ds_read_b128 v[186:189], v157
	ds_read_b128 v[190:193], v157 offset:1024
	ds_read_b128 v[194:197], v157 offset:2048
	ds_read_b128 v[198:201], v157 offset:3072
	ds_read_b128 v[202:205], v157 offset:4096
	ds_read_b128 v[206:209], v157 offset:5120
	ds_read_b128 v[210:213], v157 offset:6144
	ds_read_b128 v[214:217], v157 offset:7168
	global_load_lds_dwordx4 v[218:219], off
	v_lshl_add_u64 v[218:219], vcc, 0, v[140:141]
	s_add_i32 m0, s37, 0xe000
	s_nop 0
	global_load_lds_dwordx4 v[218:219], off
	s_waitcnt vmcnt(8)
	s_waitcnt lgkmcnt(0)
	s_barrier
	s_waitcnt lgkmcnt(0)
	v_mfma_f32_16x16x32_bf16 v[126:129], v[142:145], v[186:189], v[126:129]
	v_mfma_f32_16x16x32_bf16 v[122:125], v[162:165], v[186:189], v[122:125]
	v_mfma_f32_16x16x32_bf16 v[110:113], v[142:145], v[194:197], v[110:113]
	v_mfma_f32_16x16x32_bf16 v[106:109], v[162:165], v[194:197], v[106:109]
	v_mfma_f32_16x16x32_bf16 v[94:97], v[142:145], v[202:205], v[94:97]
	v_mfma_f32_16x16x32_bf16 v[90:93], v[162:165], v[202:205], v[90:93]
	v_mfma_f32_16x16x32_bf16 v[78:81], v[142:145], v[210:213], v[78:81]
	v_mfma_f32_16x16x32_bf16 v[74:77], v[162:165], v[210:213], v[74:77]
	v_mfma_f32_16x16x32_bf16 v[126:129], v[158:161], v[190:193], v[126:129]
	v_mfma_f32_16x16x32_bf16 v[122:125], v[166:169], v[190:193], v[122:125]
	v_mfma_f32_16x16x32_bf16 v[110:113], v[158:161], v[198:201], v[110:113]
	v_mfma_f32_16x16x32_bf16 v[106:109], v[166:169], v[198:201], v[106:109]
	v_mfma_f32_16x16x32_bf16 v[94:97], v[158:161], v[206:209], v[94:97]
	v_mfma_f32_16x16x32_bf16 v[90:93], v[166:169], v[206:209], v[90:93]
	v_mfma_f32_16x16x32_bf16 v[78:81], v[158:161], v[214:217], v[78:81]
	v_mfma_f32_16x16x32_bf16 v[74:77], v[166:169], v[214:217], v[74:77]
	v_mfma_f32_16x16x32_bf16 v[118:121], v[170:173], v[186:189], v[118:121]
	v_mfma_f32_16x16x32_bf16 v[114:117], v[178:181], v[186:189], v[114:117]
	v_mfma_f32_16x16x32_bf16 v[102:105], v[170:173], v[194:197], v[102:105]
	v_mfma_f32_16x16x32_bf16 v[98:101], v[178:181], v[194:197], v[98:101]
	v_mfma_f32_16x16x32_bf16 v[86:89], v[170:173], v[202:205], v[86:89]
	v_mfma_f32_16x16x32_bf16 v[82:85], v[178:181], v[202:205], v[82:85]
	v_mfma_f32_16x16x32_bf16 v[70:73], v[170:173], v[210:213], v[70:73]
	v_mfma_f32_16x16x32_bf16 v[66:69], v[178:181], v[210:213], v[66:69]
	v_mfma_f32_16x16x32_bf16 v[118:121], v[174:177], v[190:193], v[118:121]
	v_mfma_f32_16x16x32_bf16 v[114:117], v[182:185], v[190:193], v[114:117]
	v_mfma_f32_16x16x32_bf16 v[102:105], v[174:177], v[198:201], v[102:105]
	v_mfma_f32_16x16x32_bf16 v[98:101], v[182:185], v[198:201], v[98:101]
	v_mfma_f32_16x16x32_bf16 v[86:89], v[174:177], v[206:209], v[86:89]
	v_mfma_f32_16x16x32_bf16 v[82:85], v[182:185], v[206:209], v[82:85]
	v_mfma_f32_16x16x32_bf16 v[70:73], v[174:177], v[214:217], v[70:73]
	v_mfma_f32_16x16x32_bf16 v[66:69], v[182:185], v[214:217], v[66:69]
	s_barrier
	s_add_i32 s3, s33, s31
	v_lshl_add_u64 v[218:219], s[26:27], 0, v[132:133]
	s_mov_b32 m0, s3
	ds_read_b128 v[186:189], v157 offset:16384
	ds_read_b128 v[190:193], v157 offset:17408
	ds_read_b128 v[194:197], v157 offset:18432
	ds_read_b128 v[198:201], v157 offset:19456
	ds_read_b128 v[202:205], v157 offset:20480
	ds_read_b128 v[206:209], v157 offset:21504
	ds_read_b128 v[210:213], v157 offset:22528
	ds_read_b128 v[214:217], v157 offset:23552
	global_load_lds_dwordx4 v[218:219], off
	s_add_i32 m0, s3, 0x2000
	s_add_u32 s34, s26, 0x40000
	v_lshl_add_u64 v[220:221], s[26:27], 0, v[136:137]
	s_addc_u32 s35, s27, 0
	s_add_i32 s2, s2, s31
	global_load_lds_dwordx4 v[220:221], off
	v_lshl_add_u64 v[222:223], s[34:35], 0, v[132:133]
	s_mov_b32 m0, s2
	v_lshl_add_u64 v[224:225], s[60:61], 0, v[134:135]
	global_load_lds_dwordx4 v[222:223], off
	v_lshl_add_u64 v[222:223], s[34:35], 0, v[136:137]
	s_add_i32 m0, s2, 0x2000
	s_nop 0
	global_load_lds_dwordx4 v[222:223], off
	v_lshl_add_u64 v[222:223], s[60:61], 0, v[130:131]
	s_mov_b32 m0, s37
	s_nop 0
	global_load_lds_dwordx4 v[222:223], off
	s_mov_b32 m0, s38
	s_nop 0
	global_load_lds_dwordx4 v[224:225], off
	s_waitcnt vmcnt(8)
	s_waitcnt lgkmcnt(0)
	s_barrier
	s_waitcnt lgkmcnt(0)
	v_mfma_f32_16x16x32_bf16 v[62:65], v[142:145], v[186:189], v[62:65]
	v_mfma_f32_16x16x32_bf16 v[58:61], v[162:165], v[186:189], v[58:61]
	v_mfma_f32_16x16x32_bf16 v[46:49], v[142:145], v[194:197], v[46:49]
	v_mfma_f32_16x16x32_bf16 v[42:45], v[162:165], v[194:197], v[42:45]
	v_mfma_f32_16x16x32_bf16 v[30:33], v[142:145], v[202:205], v[30:33]
	v_mfma_f32_16x16x32_bf16 v[26:29], v[162:165], v[202:205], v[26:29]
	v_mfma_f32_16x16x32_bf16 v[14:17], v[142:145], v[210:213], v[14:17]
	v_mfma_f32_16x16x32_bf16 v[10:13], v[162:165], v[210:213], v[10:13]
	v_mfma_f32_16x16x32_bf16 v[62:65], v[158:161], v[190:193], v[62:65]
	v_mfma_f32_16x16x32_bf16 v[58:61], v[166:169], v[190:193], v[58:61]
	v_mfma_f32_16x16x32_bf16 v[46:49], v[158:161], v[198:201], v[46:49]
	v_mfma_f32_16x16x32_bf16 v[42:45], v[166:169], v[198:201], v[42:45]
	v_mfma_f32_16x16x32_bf16 v[30:33], v[158:161], v[206:209], v[30:33]
	v_mfma_f32_16x16x32_bf16 v[26:29], v[166:169], v[206:209], v[26:29]
	v_mfma_f32_16x16x32_bf16 v[14:17], v[158:161], v[214:217], v[14:17]
	v_mfma_f32_16x16x32_bf16 v[10:13], v[166:169], v[214:217], v[10:13]
	v_mfma_f32_16x16x32_bf16 v[54:57], v[170:173], v[186:189], v[54:57]
	v_mfma_f32_16x16x32_bf16 v[50:53], v[178:181], v[186:189], v[50:53]
	v_mfma_f32_16x16x32_bf16 v[38:41], v[170:173], v[194:197], v[38:41]
	v_mfma_f32_16x16x32_bf16 v[34:37], v[178:181], v[194:197], v[34:37]
	v_mfma_f32_16x16x32_bf16 v[22:25], v[170:173], v[202:205], v[22:25]
	v_mfma_f32_16x16x32_bf16 v[18:21], v[178:181], v[202:205], v[18:21]
	v_mfma_f32_16x16x32_bf16 v[6:9], v[170:173], v[210:213], v[6:9]
	v_mfma_f32_16x16x32_bf16 v[2:5], v[178:181], v[210:213], v[2:5]
	v_mfma_f32_16x16x32_bf16 v[54:57], v[174:177], v[190:193], v[54:57]
	v_mfma_f32_16x16x32_bf16 v[50:53], v[182:185], v[190:193], v[50:53]
	v_mfma_f32_16x16x32_bf16 v[38:41], v[174:177], v[198:201], v[38:41]
	v_mfma_f32_16x16x32_bf16 v[34:37], v[182:185], v[198:201], v[34:37]
	v_mfma_f32_16x16x32_bf16 v[22:25], v[174:177], v[206:209], v[22:25]
	v_mfma_f32_16x16x32_bf16 v[18:21], v[182:185], v[206:209], v[18:21]
	v_mfma_f32_16x16x32_bf16 v[6:9], v[174:177], v[214:217], v[6:9]
	v_mfma_f32_16x16x32_bf16 v[2:5], v[182:185], v[214:217], v[2:5]
	s_barrier
	s_add_i32 s2, 0, 0x18000
	v_add_u32_e32 v0, s2, v147
	s_add_i32 s3, 0, 0x1c000
	ds_read_b128 v[142:145], v0
	ds_read_b128 v[158:161], v0 offset:1024
	ds_read_b128 v[162:165], v0 offset:2048
	ds_read_b128 v[166:169], v0 offset:3072
	v_add_u32_e32 v0, s3, v147
	ds_read_b128 v[170:173], v0
	ds_read_b128 v[174:177], v0 offset:1024
	ds_read_b128 v[178:181], v0 offset:2048
	ds_read_b128 v[182:185], v0 offset:3072
	s_add_u32 s34, s60, 0x40000
	s_addc_u32 s35, s61, 0
	s_mov_b32 m0, s72
	v_lshl_add_u64 v[226:227], s[34:35], 0, v[130:131]
	ds_read_b128 v[186:189], v157 offset:32768
	ds_read_b128 v[190:193], v157 offset:33792
	ds_read_b128 v[194:197], v157 offset:34816
	ds_read_b128 v[198:201], v157 offset:35840
	ds_read_b128 v[202:205], v157 offset:36864
	ds_read_b128 v[206:209], v157 offset:37888
	ds_read_b128 v[210:213], v157 offset:38912
	ds_read_b128 v[214:217], v157 offset:39936
	global_load_lds_dwordx4 v[226:227], off
	v_lshl_add_u64 v[226:227], s[34:35], 0, v[134:135]
	s_mov_b32 m0, s73
	s_nop 0
	global_load_lds_dwordx4 v[226:227], off
	s_waitcnt vmcnt(8)
	s_waitcnt lgkmcnt(0)
	s_barrier
	s_waitcnt lgkmcnt(0)
	v_mfma_f32_16x16x32_bf16 v[126:129], v[142:145], v[186:189], v[126:129]
	v_mfma_f32_16x16x32_bf16 v[122:125], v[162:165], v[186:189], v[122:125]
	v_mfma_f32_16x16x32_bf16 v[110:113], v[142:145], v[194:197], v[110:113]
	v_mfma_f32_16x16x32_bf16 v[106:109], v[162:165], v[194:197], v[106:109]
	v_mfma_f32_16x16x32_bf16 v[94:97], v[142:145], v[202:205], v[94:97]
	v_mfma_f32_16x16x32_bf16 v[90:93], v[162:165], v[202:205], v[90:93]
	v_mfma_f32_16x16x32_bf16 v[78:81], v[142:145], v[210:213], v[78:81]
	v_mfma_f32_16x16x32_bf16 v[74:77], v[162:165], v[210:213], v[74:77]
	v_mfma_f32_16x16x32_bf16 v[126:129], v[158:161], v[190:193], v[126:129]
	v_mfma_f32_16x16x32_bf16 v[122:125], v[166:169], v[190:193], v[122:125]
	v_mfma_f32_16x16x32_bf16 v[110:113], v[158:161], v[198:201], v[110:113]
	v_mfma_f32_16x16x32_bf16 v[106:109], v[166:169], v[198:201], v[106:109]
	v_mfma_f32_16x16x32_bf16 v[94:97], v[158:161], v[206:209], v[94:97]
	v_mfma_f32_16x16x32_bf16 v[90:93], v[166:169], v[206:209], v[90:93]
	v_mfma_f32_16x16x32_bf16 v[78:81], v[158:161], v[214:217], v[78:81]
	v_mfma_f32_16x16x32_bf16 v[74:77], v[166:169], v[214:217], v[74:77]
	v_mfma_f32_16x16x32_bf16 v[118:121], v[170:173], v[186:189], v[118:121]
	v_mfma_f32_16x16x32_bf16 v[114:117], v[178:181], v[186:189], v[114:117]
	v_mfma_f32_16x16x32_bf16 v[102:105], v[170:173], v[194:197], v[102:105]
	v_mfma_f32_16x16x32_bf16 v[98:101], v[178:181], v[194:197], v[98:101]
	v_mfma_f32_16x16x32_bf16 v[86:89], v[170:173], v[202:205], v[86:89]
	v_mfma_f32_16x16x32_bf16 v[82:85], v[178:181], v[202:205], v[82:85]
	v_mfma_f32_16x16x32_bf16 v[70:73], v[170:173], v[210:213], v[70:73]
	v_mfma_f32_16x16x32_bf16 v[66:69], v[178:181], v[210:213], v[66:69]
	v_mfma_f32_16x16x32_bf16 v[118:121], v[174:177], v[190:193], v[118:121]
	v_mfma_f32_16x16x32_bf16 v[114:117], v[182:185], v[190:193], v[114:117]
	v_mfma_f32_16x16x32_bf16 v[102:105], v[174:177], v[198:201], v[102:105]
	v_mfma_f32_16x16x32_bf16 v[98:101], v[182:185], v[198:201], v[98:101]
	v_mfma_f32_16x16x32_bf16 v[86:89], v[174:177], v[206:209], v[86:89]
	v_mfma_f32_16x16x32_bf16 v[82:85], v[182:185], v[206:209], v[82:85]
	v_mfma_f32_16x16x32_bf16 v[70:73], v[174:177], v[214:217], v[70:73]
	v_mfma_f32_16x16x32_bf16 v[66:69], v[182:185], v[214:217], v[66:69]
	s_barrier
	s_add_i32 s2, s2, s31
	v_lshl_add_u64 v[218:219], v[218:219], 0, s[74:75]
	s_mov_b32 m0, s2
	ds_read_b128 v[186:189], v157 offset:49152
	ds_read_b128 v[190:193], v157 offset:50176
	ds_read_b128 v[194:197], v157 offset:51200
	ds_read_b128 v[198:201], v157 offset:52224
	ds_read_b128 v[202:205], v157 offset:53248
	ds_read_b128 v[206:209], v157 offset:54272
	ds_read_b128 v[210:213], v157 offset:55296
	ds_read_b128 v[214:217], v157 offset:56320
	global_load_lds_dwordx4 v[218:219], off
	s_add_i32 m0, s2, 0x2000
	s_add_u32 s26, s26, 0x40080
	v_lshl_add_u64 v[218:219], v[220:221], 0, s[74:75]
	s_addc_u32 s27, s27, 0
	s_add_i32 s2, s3, s31
	global_load_lds_dwordx4 v[218:219], off
	v_lshl_add_u64 v[218:219], s[26:27], 0, v[132:133]
	s_mov_b32 m0, s2
	s_nop 0
	global_load_lds_dwordx4 v[218:219], off
	v_lshl_add_u64 v[218:219], s[26:27], 0, v[136:137]
	s_add_i32 m0, s2, 0x2000
	s_nop 0
	global_load_lds_dwordx4 v[218:219], off
	v_lshl_add_u64 v[218:219], v[222:223], 0, s[74:75]
	s_mov_b32 m0, s76
	s_nop 0
	global_load_lds_dwordx4 v[218:219], off
	v_lshl_add_u64 v[218:219], v[224:225], 0, s[74:75]
	s_mov_b32 m0, s77
	s_nop 0
	global_load_lds_dwordx4 v[218:219], off
	s_waitcnt vmcnt(8)
	s_waitcnt lgkmcnt(0)
	s_barrier
	s_waitcnt lgkmcnt(0)
	v_mfma_f32_16x16x32_bf16 v[62:65], v[142:145], v[186:189], v[62:65]
	v_mfma_f32_16x16x32_bf16 v[58:61], v[162:165], v[186:189], v[58:61]
	v_mfma_f32_16x16x32_bf16 v[46:49], v[142:145], v[194:197], v[46:49]
	v_mfma_f32_16x16x32_bf16 v[42:45], v[162:165], v[194:197], v[42:45]
	v_mfma_f32_16x16x32_bf16 v[30:33], v[142:145], v[202:205], v[30:33]
	v_mfma_f32_16x16x32_bf16 v[26:29], v[162:165], v[202:205], v[26:29]
	v_mfma_f32_16x16x32_bf16 v[14:17], v[142:145], v[210:213], v[14:17]
	v_mfma_f32_16x16x32_bf16 v[10:13], v[162:165], v[210:213], v[10:13]
	v_mfma_f32_16x16x32_bf16 v[62:65], v[158:161], v[190:193], v[62:65]
	v_mfma_f32_16x16x32_bf16 v[58:61], v[166:169], v[190:193], v[58:61]
	v_mfma_f32_16x16x32_bf16 v[46:49], v[158:161], v[198:201], v[46:49]
	v_mfma_f32_16x16x32_bf16 v[42:45], v[166:169], v[198:201], v[42:45]
	v_mfma_f32_16x16x32_bf16 v[30:33], v[158:161], v[206:209], v[30:33]
	v_mfma_f32_16x16x32_bf16 v[26:29], v[166:169], v[206:209], v[26:29]
	v_mfma_f32_16x16x32_bf16 v[14:17], v[158:161], v[214:217], v[14:17]
	v_mfma_f32_16x16x32_bf16 v[10:13], v[166:169], v[214:217], v[10:13]
	v_mfma_f32_16x16x32_bf16 v[54:57], v[170:173], v[186:189], v[54:57]
	v_mfma_f32_16x16x32_bf16 v[50:53], v[178:181], v[186:189], v[50:53]
	v_mfma_f32_16x16x32_bf16 v[38:41], v[170:173], v[194:197], v[38:41]
	v_mfma_f32_16x16x32_bf16 v[34:37], v[178:181], v[194:197], v[34:37]
	v_mfma_f32_16x16x32_bf16 v[22:25], v[170:173], v[202:205], v[22:25]
	v_mfma_f32_16x16x32_bf16 v[18:21], v[178:181], v[202:205], v[18:21]
	v_mfma_f32_16x16x32_bf16 v[6:9], v[170:173], v[210:213], v[6:9]
	v_mfma_f32_16x16x32_bf16 v[2:5], v[178:181], v[210:213], v[2:5]
	v_mfma_f32_16x16x32_bf16 v[54:57], v[174:177], v[190:193], v[54:57]
	v_mfma_f32_16x16x32_bf16 v[50:53], v[182:185], v[190:193], v[50:53]
	v_mfma_f32_16x16x32_bf16 v[38:41], v[174:177], v[198:201], v[38:41]
	v_mfma_f32_16x16x32_bf16 v[34:37], v[182:185], v[198:201], v[34:37]
	v_mfma_f32_16x16x32_bf16 v[22:25], v[174:177], v[206:209], v[22:25]
	v_mfma_f32_16x16x32_bf16 v[18:21], v[182:185], v[206:209], v[18:21]
	v_mfma_f32_16x16x32_bf16 v[6:9], v[174:177], v[214:217], v[6:9]
	v_mfma_f32_16x16x32_bf16 v[2:5], v[182:185], v[214:217], v[2:5]
	s_barrier
	s_add_i32 s71, s71, 2
	s_add_u32 vcc_lo, vcc_lo, 0x100
	s_addc_u32 vcc_hi, vcc_hi, 0
	s_add_u32 s81, s81, 0x100
	s_addc_u32 s82, s82, 0
	s_cmp_gt_u32 s71, 13
	s_cbranch_scc0 .LBB0_1962
	s_and_b64 vcc, exec, s[10:11]
	s_cbranch_vccz .LBB0_1965
	s_barrier
